# GEMM MFMA order G7: row-snake over (m,q) at k0 then column-snake at k1: 30 operand-shared transitions, 1 forwarded accumulator per segment
# baseline (speedup 1.0000x reference)
.LBB0_200:
	ds_read_b128 v[148:151], v169
	ds_read_b128 v[152:155], v169 offset:1024
	ds_read_b128 v[156:159], v169 offset:2048
	ds_read_b128 v[160:163], v169 offset:3072
	ds_read_b128 v[174:177], v170
	ds_read_b128 v[178:181], v170 offset:1024
	ds_read_b128 v[182:185], v170 offset:2048
	ds_read_b128 v[186:189], v170 offset:3072
	s_add_u32 s26, s6, 0xfff00800
	s_addc_u32 s27, s7, -1
	s_cmp_eq_u32 s34, 60
	s_cselect_b32 s29, s17, s27
	s_cselect_b32 s28, s23, s26
	s_cselect_b32 s27, s15, s31
	s_cselect_b32 s26, s25, s30
	v_lshl_add_u64 v[190:191], s[6:7], 0, v[138:139]
	s_add_i32 m0, s41, 0xc000
	s_nop 0
	global_load_lds_dwordx4 v[190:191], off
	v_lshl_add_u64 v[190:191], s[6:7], 0, v[140:141]
	s_add_i32 m0, s41, 0xe000
	s_nop 0
	global_load_lds_dwordx4 v[190:191], off
	ds_read_b128 v[190:193], v171
	ds_read_b128 v[194:197], v171 offset:1024
	ds_read_b128 v[198:201], v171 offset:2048
	ds_read_b128 v[202:205], v171 offset:3072
	ds_read_b128 v[206:209], v171 offset:4096
	ds_read_b128 v[210:213], v171 offset:5120
	ds_read_b128 v[214:217], v171 offset:6144
	ds_read_b128 v[218:221], v171 offset:7168
	s_waitcnt vmcnt(8)
	s_waitcnt lgkmcnt(0)
	s_barrier
	s_waitcnt lgkmcnt(0)
	v_mfma_f32_16x16x32_bf16 v[124:127], v[148:151], v[190:193], v[124:127]
	v_mfma_f32_16x16x32_bf16 v[120:123], v[156:159], v[190:193], v[120:123]
	v_mfma_f32_16x16x32_bf16 v[60:63], v[174:177], v[190:193], v[60:63]
	v_mfma_f32_16x16x32_bf16 v[56:59], v[182:185], v[190:193], v[56:59]
	v_mfma_f32_16x16x32_bf16 v[48:51], v[182:185], v[198:201], v[48:51]
	v_mfma_f32_16x16x32_bf16 v[52:55], v[174:177], v[198:201], v[52:55]
	v_mfma_f32_16x16x32_bf16 v[112:115], v[156:159], v[198:201], v[112:115]
	v_mfma_f32_16x16x32_bf16 v[116:119], v[148:151], v[198:201], v[116:119]
	v_mfma_f32_16x16x32_bf16 v[108:111], v[148:151], v[206:209], v[108:111]
	v_mfma_f32_16x16x32_bf16 v[104:107], v[156:159], v[206:209], v[104:107]
	v_mfma_f32_16x16x32_bf16 v[44:47], v[174:177], v[206:209], v[44:47]
	v_mfma_f32_16x16x32_bf16 v[40:43], v[182:185], v[206:209], v[40:43]
	v_mfma_f32_16x16x32_bf16 v[32:35], v[182:185], v[214:217], v[32:35]
	v_mfma_f32_16x16x32_bf16 v[36:39], v[174:177], v[214:217], v[36:39]
	v_mfma_f32_16x16x32_bf16 v[96:99], v[156:159], v[214:217], v[96:99]
	v_mfma_f32_16x16x32_bf16 v[100:103], v[148:151], v[214:217], v[100:103]
	v_mfma_f32_16x16x32_bf16 v[100:103], v[152:155], v[218:221], v[100:103]
	v_mfma_f32_16x16x32_bf16 v[108:111], v[152:155], v[210:213], v[108:111]
	v_mfma_f32_16x16x32_bf16 v[116:119], v[152:155], v[202:205], v[116:119]
	v_mfma_f32_16x16x32_bf16 v[124:127], v[152:155], v[194:197], v[124:127]
	v_mfma_f32_16x16x32_bf16 v[120:123], v[160:163], v[194:197], v[120:123]
	v_mfma_f32_16x16x32_bf16 v[112:115], v[160:163], v[202:205], v[112:115]
	v_mfma_f32_16x16x32_bf16 v[104:107], v[160:163], v[210:213], v[104:107]
	v_mfma_f32_16x16x32_bf16 v[96:99], v[160:163], v[218:221], v[96:99]
	v_mfma_f32_16x16x32_bf16 v[36:39], v[178:181], v[218:221], v[36:39]
	v_mfma_f32_16x16x32_bf16 v[44:47], v[178:181], v[210:213], v[44:47]
	v_mfma_f32_16x16x32_bf16 v[52:55], v[178:181], v[202:205], v[52:55]
	v_mfma_f32_16x16x32_bf16 v[60:63], v[178:181], v[194:197], v[60:63]
	v_mfma_f32_16x16x32_bf16 v[56:59], v[186:189], v[194:197], v[56:59]
	v_mfma_f32_16x16x32_bf16 v[48:51], v[186:189], v[202:205], v[48:51]
	v_mfma_f32_16x16x32_bf16 v[40:43], v[186:189], v[210:213], v[40:43]
	v_mfma_f32_16x16x32_bf16 v[32:35], v[186:189], v[218:221], v[32:35]
	s_barrier
	s_add_i32 s35, s55, s36
	v_lshl_add_u64 v[222:223], s[26:27], 0, v[130:131]
	s_mov_b32 m0, s35
	v_lshl_add_u64 v[224:225], s[26:27], 0, v[134:135]
	global_load_lds_dwordx4 v[222:223], off
	s_add_i32 m0, s35, 0x2000
	s_add_u32 s58, s26, 0x100000
	s_addc_u32 s59, s27, 0
	s_add_i32 s35, s56, s36
	global_load_lds_dwordx4 v[224:225], off
	v_lshl_add_u64 v[190:191], s[58:59], 0, v[130:131]
	s_mov_b32 m0, s35
	v_lshl_add_u64 v[226:227], s[28:29], 0, v[128:129]
	global_load_lds_dwordx4 v[190:191], off
	v_lshl_add_u64 v[190:191], s[58:59], 0, v[134:135]
	s_add_i32 m0, s35, 0x2000
	v_lshl_add_u64 v[228:229], s[28:29], 0, v[132:133]
	global_load_lds_dwordx4 v[190:191], off
	s_mov_b32 m0, s41
	s_nop 0
	global_load_lds_dwordx4 v[226:227], off
	s_mov_b32 m0, s42
	s_nop 0
	global_load_lds_dwordx4 v[228:229], off
	ds_read_b128 v[190:193], v171 offset:16384
	ds_read_b128 v[194:197], v171 offset:17408
	ds_read_b128 v[198:201], v171 offset:18432
	ds_read_b128 v[202:205], v171 offset:19456
	ds_read_b128 v[206:209], v171 offset:20480
	ds_read_b128 v[210:213], v171 offset:21504
	ds_read_b128 v[214:217], v171 offset:22528
	ds_read_b128 v[218:221], v171 offset:23552
	s_waitcnt vmcnt(8)
	s_waitcnt lgkmcnt(0)
	s_barrier
	s_waitcnt lgkmcnt(0)
	v_mfma_f32_16x16x32_bf16 v[92:95], v[148:151], v[190:193], v[92:95]
	v_mfma_f32_16x16x32_bf16 v[88:91], v[156:159], v[190:193], v[88:91]
	v_mfma_f32_16x16x32_bf16 v[28:31], v[174:177], v[190:193], v[28:31]
	v_mfma_f32_16x16x32_bf16 v[24:27], v[182:185], v[190:193], v[24:27]
	v_mfma_f32_16x16x32_bf16 v[16:19], v[182:185], v[198:201], v[16:19]
	v_mfma_f32_16x16x32_bf16 v[20:23], v[174:177], v[198:201], v[20:23]
	v_mfma_f32_16x16x32_bf16 v[80:83], v[156:159], v[198:201], v[80:83]
	v_mfma_f32_16x16x32_bf16 v[84:87], v[148:151], v[198:201], v[84:87]
	v_mfma_f32_16x16x32_bf16 v[76:79], v[148:151], v[206:209], v[76:79]
	v_mfma_f32_16x16x32_bf16 v[72:75], v[156:159], v[206:209], v[72:75]
	v_mfma_f32_16x16x32_bf16 v[12:15], v[174:177], v[206:209], v[12:15]
	v_mfma_f32_16x16x32_bf16 v[8:11], v[182:185], v[206:209], v[8:11]
	v_mfma_f32_16x16x32_bf16 v[0:3], v[182:185], v[214:217], v[0:3]
	v_mfma_f32_16x16x32_bf16 v[4:7], v[174:177], v[214:217], v[4:7]
	v_mfma_f32_16x16x32_bf16 v[64:67], v[156:159], v[214:217], v[64:67]
	v_mfma_f32_16x16x32_bf16 v[68:71], v[148:151], v[214:217], v[68:71]
	v_mfma_f32_16x16x32_bf16 v[68:71], v[152:155], v[218:221], v[68:71]
	v_mfma_f32_16x16x32_bf16 v[76:79], v[152:155], v[210:213], v[76:79]
	v_mfma_f32_16x16x32_bf16 v[84:87], v[152:155], v[202:205], v[84:87]
	v_mfma_f32_16x16x32_bf16 v[92:95], v[152:155], v[194:197], v[92:95]
	v_mfma_f32_16x16x32_bf16 v[88:91], v[160:163], v[194:197], v[88:91]
	v_mfma_f32_16x16x32_bf16 v[80:83], v[160:163], v[202:205], v[80:83]
	v_mfma_f32_16x16x32_bf16 v[72:75], v[160:163], v[210:213], v[72:75]
	v_mfma_f32_16x16x32_bf16 v[64:67], v[160:163], v[218:221], v[64:67]
	v_mfma_f32_16x16x32_bf16 v[4:7], v[178:181], v[218:221], v[4:7]
	v_mfma_f32_16x16x32_bf16 v[12:15], v[178:181], v[210:213], v[12:15]
	v_mfma_f32_16x16x32_bf16 v[20:23], v[178:181], v[202:205], v[20:23]
	v_mfma_f32_16x16x32_bf16 v[28:31], v[178:181], v[194:197], v[28:31]
	v_mfma_f32_16x16x32_bf16 v[24:27], v[186:189], v[194:197], v[24:27]
	v_mfma_f32_16x16x32_bf16 v[16:19], v[186:189], v[202:205], v[16:19]
	v_mfma_f32_16x16x32_bf16 v[8:11], v[186:189], v[210:213], v[8:11]
	v_mfma_f32_16x16x32_bf16 v[0:3], v[186:189], v[218:221], v[0:3]
	s_barrier
	s_add_i32 s35, 0, 0x18000
	v_add_u32_e32 v136, s35, v165
	s_add_i32 s57, 0, 0x1c000
	ds_read_b128 v[148:151], v136
	ds_read_b128 v[152:155], v136 offset:1024
	ds_read_b128 v[156:159], v136 offset:2048
	ds_read_b128 v[160:163], v136 offset:3072
	v_add_u32_e32 v136, s57, v165
	ds_read_b128 v[174:177], v136
	ds_read_b128 v[178:181], v136 offset:1024
	ds_read_b128 v[182:185], v136 offset:2048
	ds_read_b128 v[186:189], v136 offset:3072
	s_add_u32 s28, s28, 0x100000
	s_addc_u32 s29, s29, 0
	s_mov_b32 m0, s43
	v_lshl_add_u64 v[190:191], s[28:29], 0, v[128:129]
	global_load_lds_dwordx4 v[190:191], off
	v_lshl_add_u64 v[190:191], s[28:29], 0, v[132:133]
	s_mov_b32 m0, s44
	s_nop 0
	global_load_lds_dwordx4 v[190:191], off
	ds_read_b128 v[190:193], v171 offset:32768
	ds_read_b128 v[194:197], v171 offset:33792
	ds_read_b128 v[198:201], v171 offset:34816
	ds_read_b128 v[202:205], v171 offset:35840
	ds_read_b128 v[206:209], v171 offset:36864
	ds_read_b128 v[210:213], v171 offset:37888
	ds_read_b128 v[214:217], v171 offset:38912
	ds_read_b128 v[218:221], v171 offset:39936
	s_waitcnt vmcnt(8)
	s_waitcnt lgkmcnt(0)
	s_barrier
	s_waitcnt lgkmcnt(0)
	v_mfma_f32_16x16x32_bf16 v[124:127], v[148:151], v[190:193], v[124:127]
	v_mfma_f32_16x16x32_bf16 v[120:123], v[156:159], v[190:193], v[120:123]
	v_mfma_f32_16x16x32_bf16 v[60:63], v[174:177], v[190:193], v[60:63]
	v_mfma_f32_16x16x32_bf16 v[56:59], v[182:185], v[190:193], v[56:59]
	v_mfma_f32_16x16x32_bf16 v[48:51], v[182:185], v[198:201], v[48:51]
	v_mfma_f32_16x16x32_bf16 v[52:55], v[174:177], v[198:201], v[52:55]
	v_mfma_f32_16x16x32_bf16 v[112:115], v[156:159], v[198:201], v[112:115]
	v_mfma_f32_16x16x32_bf16 v[116:119], v[148:151], v[198:201], v[116:119]
	v_mfma_f32_16x16x32_bf16 v[108:111], v[148:151], v[206:209], v[108:111]
	v_mfma_f32_16x16x32_bf16 v[104:107], v[156:159], v[206:209], v[104:107]
	v_mfma_f32_16x16x32_bf16 v[44:47], v[174:177], v[206:209], v[44:47]
	v_mfma_f32_16x16x32_bf16 v[40:43], v[182:185], v[206:209], v[40:43]
	v_mfma_f32_16x16x32_bf16 v[32:35], v[182:185], v[214:217], v[32:35]
	v_mfma_f32_16x16x32_bf16 v[36:39], v[174:177], v[214:217], v[36:39]
	v_mfma_f32_16x16x32_bf16 v[96:99], v[156:159], v[214:217], v[96:99]
	v_mfma_f32_16x16x32_bf16 v[100:103], v[148:151], v[214:217], v[100:103]
	v_mfma_f32_16x16x32_bf16 v[100:103], v[152:155], v[218:221], v[100:103]
	v_mfma_f32_16x16x32_bf16 v[108:111], v[152:155], v[210:213], v[108:111]
	v_mfma_f32_16x16x32_bf16 v[116:119], v[152:155], v[202:205], v[116:119]
	v_mfma_f32_16x16x32_bf16 v[124:127], v[152:155], v[194:197], v[124:127]
	v_mfma_f32_16x16x32_bf16 v[120:123], v[160:163], v[194:197], v[120:123]
	v_mfma_f32_16x16x32_bf16 v[112:115], v[160:163], v[202:205], v[112:115]
	v_mfma_f32_16x16x32_bf16 v[104:107], v[160:163], v[210:213], v[104:107]
	v_mfma_f32_16x16x32_bf16 v[96:99], v[160:163], v[218:221], v[96:99]
	v_mfma_f32_16x16x32_bf16 v[36:39], v[178:181], v[218:221], v[36:39]
	v_mfma_f32_16x16x32_bf16 v[44:47], v[178:181], v[210:213], v[44:47]
	v_mfma_f32_16x16x32_bf16 v[52:55], v[178:181], v[202:205], v[52:55]
	v_mfma_f32_16x16x32_bf16 v[60:63], v[178:181], v[194:197], v[60:63]
	v_mfma_f32_16x16x32_bf16 v[56:59], v[186:189], v[194:197], v[56:59]
	v_mfma_f32_16x16x32_bf16 v[48:51], v[186:189], v[202:205], v[48:51]
	v_mfma_f32_16x16x32_bf16 v[40:43], v[186:189], v[210:213], v[40:43]
	v_mfma_f32_16x16x32_bf16 v[32:35], v[186:189], v[218:221], v[32:35]
	s_barrier
	s_add_i32 s28, s35, s36
	v_lshl_add_u64 v[190:191], v[222:223], 0, s[12:13]
	s_mov_b32 m0, s28
	s_nop 0
	global_load_lds_dwordx4 v[190:191], off
	s_add_i32 m0, s28, 0x2000
	s_add_u32 s26, s26, 0x100800
	v_lshl_add_u64 v[190:191], v[224:225], 0, s[12:13]
	s_addc_u32 s27, s27, 0
	s_add_i32 s28, s57, s36
	global_load_lds_dwordx4 v[190:191], off
	v_lshl_add_u64 v[190:191], s[26:27], 0, v[130:131]
	s_mov_b32 m0, s28
	s_nop 0
	global_load_lds_dwordx4 v[190:191], off
	v_lshl_add_u64 v[190:191], s[26:27], 0, v[134:135]
	s_add_i32 m0, s28, 0x2000
	s_nop 0
	global_load_lds_dwordx4 v[190:191], off
	v_lshl_add_u64 v[190:191], v[226:227], 0, s[12:13]
	s_mov_b32 m0, s49
	s_nop 0
	global_load_lds_dwordx4 v[190:191], off
	v_lshl_add_u64 v[190:191], v[228:229], 0, s[12:13]
	s_mov_b32 m0, s50
	s_nop 0
	global_load_lds_dwordx4 v[190:191], off
	ds_read_b128 v[190:193], v171 offset:49152
	ds_read_b128 v[194:197], v171 offset:50176
	ds_read_b128 v[198:201], v171 offset:51200
	ds_read_b128 v[202:205], v171 offset:52224
	ds_read_b128 v[206:209], v171 offset:53248
	ds_read_b128 v[210:213], v171 offset:54272
	ds_read_b128 v[214:217], v171 offset:55296
	ds_read_b128 v[218:221], v171 offset:56320
	s_waitcnt vmcnt(8)
	s_waitcnt lgkmcnt(0)
	s_barrier
	s_waitcnt lgkmcnt(0)
	v_mfma_f32_16x16x32_bf16 v[92:95], v[148:151], v[190:193], v[92:95]
	v_mfma_f32_16x16x32_bf16 v[88:91], v[156:159], v[190:193], v[88:91]
	v_mfma_f32_16x16x32_bf16 v[28:31], v[174:177], v[190:193], v[28:31]
	v_mfma_f32_16x16x32_bf16 v[24:27], v[182:185], v[190:193], v[24:27]
	v_mfma_f32_16x16x32_bf16 v[16:19], v[182:185], v[198:201], v[16:19]
	v_mfma_f32_16x16x32_bf16 v[20:23], v[174:177], v[198:201], v[20:23]
	v_mfma_f32_16x16x32_bf16 v[80:83], v[156:159], v[198:201], v[80:83]
	v_mfma_f32_16x16x32_bf16 v[84:87], v[148:151], v[198:201], v[84:87]
	v_mfma_f32_16x16x32_bf16 v[76:79], v[148:151], v[206:209], v[76:79]
	v_mfma_f32_16x16x32_bf16 v[72:75], v[156:159], v[206:209], v[72:75]
	v_mfma_f32_16x16x32_bf16 v[12:15], v[174:177], v[206:209], v[12:15]
	v_mfma_f32_16x16x32_bf16 v[8:11], v[182:185], v[206:209], v[8:11]
	v_mfma_f32_16x16x32_bf16 v[0:3], v[182:185], v[214:217], v[0:3]
	v_mfma_f32_16x16x32_bf16 v[4:7], v[174:177], v[214:217], v[4:7]
	v_mfma_f32_16x16x32_bf16 v[64:67], v[156:159], v[214:217], v[64:67]
	v_mfma_f32_16x16x32_bf16 v[68:71], v[148:151], v[214:217], v[68:71]
	v_mfma_f32_16x16x32_bf16 v[68:71], v[152:155], v[218:221], v[68:71]
	v_mfma_f32_16x16x32_bf16 v[76:79], v[152:155], v[210:213], v[76:79]
	v_mfma_f32_16x16x32_bf16 v[84:87], v[152:155], v[202:205], v[84:87]
	v_mfma_f32_16x16x32_bf16 v[92:95], v[152:155], v[194:197], v[92:95]
	v_mfma_f32_16x16x32_bf16 v[88:91], v[160:163], v[194:197], v[88:91]
	v_mfma_f32_16x16x32_bf16 v[80:83], v[160:163], v[202:205], v[80:83]
	v_mfma_f32_16x16x32_bf16 v[72:75], v[160:163], v[210:213], v[72:75]
	v_mfma_f32_16x16x32_bf16 v[64:67], v[160:163], v[218:221], v[64:67]
	v_mfma_f32_16x16x32_bf16 v[4:7], v[178:181], v[218:221], v[4:7]
	v_mfma_f32_16x16x32_bf16 v[12:15], v[178:181], v[210:213], v[12:15]
	v_mfma_f32_16x16x32_bf16 v[20:23], v[178:181], v[202:205], v[20:23]
	v_mfma_f32_16x16x32_bf16 v[28:31], v[178:181], v[194:197], v[28:31]
	v_mfma_f32_16x16x32_bf16 v[24:27], v[186:189], v[194:197], v[24:27]
	v_mfma_f32_16x16x32_bf16 v[16:19], v[186:189], v[202:205], v[16:19]
	v_mfma_f32_16x16x32_bf16 v[8:11], v[186:189], v[210:213], v[8:11]
	v_mfma_f32_16x16x32_bf16 v[0:3], v[186:189], v[218:221], v[0:3]
	s_barrier
	s_add_i32 s34, s34, 2
	s_add_u32 s6, s6, 0x1000
	s_addc_u32 s7, s7, 0
	s_add_u32 s30, s30, 0x1000
	s_addc_u32 s31, s31, 0
	s_cmp_gt_u32 s34, 61
	s_cbranch_scc0 .LBB0_200
	s_and_b64 vcc, exec, s[0:1]
	s_cbranch_vccz .LBB0_203
	s_barrier

.LBB0_333:
	ds_read_b128 v[144:147], v152
	ds_read_b128 v[156:159], v152 offset:1024
	ds_read_b128 v[160:163], v152 offset:2048
	ds_read_b128 v[164:167], v152 offset:3072
	ds_read_b128 v[168:171], v153
	ds_read_b128 v[172:175], v153 offset:1024
	ds_read_b128 v[176:179], v153 offset:2048
	ds_read_b128 v[180:183], v153 offset:3072
	s_add_u32 s28, s24, 0x100
	s_addc_u32 s29, s25, 0
	s_cmp_eq_u32 s56, 60
	s_cselect_b32 s35, s13, s29
	s_cselect_b32 s34, s52, s28
	s_cselect_b32 s31, s11, s55
	s_cselect_b32 s30, s53, s54
	v_lshl_add_u64 v[184:185], s[24:25], 0, v[136:137]
	s_add_i32 m0, s21, 0xc000
	s_nop 0
	global_load_lds_dwordx4 v[184:185], off
	v_lshl_add_u64 v[184:185], s[24:25], 0, v[138:139]
	s_add_i32 m0, s21, 0xe000
	s_nop 0
	global_load_lds_dwordx4 v[184:185], off
	ds_read_b128 v[184:187], v154
	ds_read_b128 v[188:191], v154 offset:1024
	ds_read_b128 v[192:195], v154 offset:2048
	ds_read_b128 v[196:199], v154 offset:3072
	ds_read_b128 v[200:203], v154 offset:4096
	ds_read_b128 v[204:207], v154 offset:5120
	ds_read_b128 v[208:211], v154 offset:6144
	ds_read_b128 v[212:215], v154 offset:7168
	s_waitcnt vmcnt(8)
	s_waitcnt lgkmcnt(0)
	s_barrier
	s_waitcnt lgkmcnt(0)
	v_mfma_f32_16x16x32_bf16 v[124:127], v[144:147], v[184:187], v[124:127]
	v_mfma_f32_16x16x32_bf16 v[120:123], v[160:163], v[184:187], v[120:123]
	v_mfma_f32_16x16x32_bf16 v[112:115], v[168:171], v[184:187], v[112:115]
	v_mfma_f32_16x16x32_bf16 v[104:107], v[176:179], v[184:187], v[104:107]
	v_mfma_f32_16x16x32_bf16 v[88:91], v[176:179], v[192:195], v[88:91]
	v_mfma_f32_16x16x32_bf16 v[96:99], v[168:171], v[192:195], v[96:99]
	v_mfma_f32_16x16x32_bf16 v[108:111], v[160:163], v[192:195], v[108:111]
	v_mfma_f32_16x16x32_bf16 v[116:119], v[144:147], v[192:195], v[116:119]
	v_mfma_f32_16x16x32_bf16 v[100:103], v[144:147], v[200:203], v[100:103]
	v_mfma_f32_16x16x32_bf16 v[92:95], v[160:163], v[200:203], v[92:95]
	v_mfma_f32_16x16x32_bf16 v[80:83], v[168:171], v[200:203], v[80:83]
	v_mfma_f32_16x16x32_bf16 v[72:75], v[176:179], v[200:203], v[72:75]
	v_mfma_f32_16x16x32_bf16 v[64:67], v[176:179], v[208:211], v[64:67]
	v_mfma_f32_16x16x32_bf16 v[68:71], v[168:171], v[208:211], v[68:71]
	v_mfma_f32_16x16x32_bf16 v[76:79], v[160:163], v[208:211], v[76:79]
	v_mfma_f32_16x16x32_bf16 v[84:87], v[144:147], v[208:211], v[84:87]
	v_mfma_f32_16x16x32_bf16 v[84:87], v[156:159], v[212:215], v[84:87]
	v_mfma_f32_16x16x32_bf16 v[100:103], v[156:159], v[204:207], v[100:103]
	v_mfma_f32_16x16x32_bf16 v[116:119], v[156:159], v[196:199], v[116:119]
	v_mfma_f32_16x16x32_bf16 v[124:127], v[156:159], v[188:191], v[124:127]
	v_mfma_f32_16x16x32_bf16 v[120:123], v[164:167], v[188:191], v[120:123]
	v_mfma_f32_16x16x32_bf16 v[108:111], v[164:167], v[196:199], v[108:111]
	v_mfma_f32_16x16x32_bf16 v[92:95], v[164:167], v[204:207], v[92:95]
	v_mfma_f32_16x16x32_bf16 v[76:79], v[164:167], v[212:215], v[76:79]
	v_mfma_f32_16x16x32_bf16 v[68:71], v[172:175], v[212:215], v[68:71]
	v_mfma_f32_16x16x32_bf16 v[80:83], v[172:175], v[204:207], v[80:83]
	v_mfma_f32_16x16x32_bf16 v[96:99], v[172:175], v[196:199], v[96:99]
	v_mfma_f32_16x16x32_bf16 v[112:115], v[172:175], v[188:191], v[112:115]
	v_mfma_f32_16x16x32_bf16 v[104:107], v[180:183], v[188:191], v[104:107]
	v_mfma_f32_16x16x32_bf16 v[88:91], v[180:183], v[196:199], v[88:91]
	v_mfma_f32_16x16x32_bf16 v[72:75], v[180:183], v[204:207], v[72:75]
	v_mfma_f32_16x16x32_bf16 v[64:67], v[180:183], v[212:215], v[64:67]
	s_barrier
	s_add_i32 s24, s49, s41
	v_lshl_add_u64 v[216:217], s[30:31], 0, v[130:131]
	s_mov_b32 m0, s24
	v_lshl_add_u64 v[218:219], s[30:31], 0, v[134:135]
	global_load_lds_dwordx4 v[216:217], off
	s_add_i32 m0, s24, 0x2000
	s_add_u32 s24, s30, 0x100000
	s_addc_u32 s25, s31, 0
	s_add_i32 s57, s50, s41
	global_load_lds_dwordx4 v[218:219], off
	v_lshl_add_u64 v[184:185], s[24:25], 0, v[130:131]
	s_mov_b32 m0, s57
	v_lshl_add_u64 v[220:221], s[34:35], 0, v[128:129]
	global_load_lds_dwordx4 v[184:185], off
	v_lshl_add_u64 v[184:185], s[24:25], 0, v[134:135]
	s_add_i32 m0, s57, 0x2000
	v_lshl_add_u64 v[222:223], s[34:35], 0, v[132:133]
	global_load_lds_dwordx4 v[184:185], off
	s_mov_b32 m0, s21
	s_nop 0
	global_load_lds_dwordx4 v[220:221], off
	s_mov_b32 m0, s42
	s_nop 0
	global_load_lds_dwordx4 v[222:223], off
	ds_read_b128 v[184:187], v154 offset:16384
	ds_read_b128 v[188:191], v154 offset:17408
	ds_read_b128 v[192:195], v154 offset:18432
	ds_read_b128 v[196:199], v154 offset:19456
	ds_read_b128 v[200:203], v154 offset:20480
	ds_read_b128 v[204:207], v154 offset:21504
	ds_read_b128 v[208:211], v154 offset:22528
	ds_read_b128 v[212:215], v154 offset:23552
	s_waitcnt vmcnt(8)
	s_waitcnt lgkmcnt(0)
	s_barrier
	s_waitcnt lgkmcnt(0)
	v_mfma_f32_16x16x32_bf16 v[60:63], v[144:147], v[184:187], v[60:63]
	v_mfma_f32_16x16x32_bf16 v[56:59], v[160:163], v[184:187], v[56:59]
	v_mfma_f32_16x16x32_bf16 v[48:51], v[168:171], v[184:187], v[48:51]
	v_mfma_f32_16x16x32_bf16 v[40:43], v[176:179], v[184:187], v[40:43]
	v_mfma_f32_16x16x32_bf16 v[24:27], v[176:179], v[192:195], v[24:27]
	v_mfma_f32_16x16x32_bf16 v[32:35], v[168:171], v[192:195], v[32:35]
	v_mfma_f32_16x16x32_bf16 v[44:47], v[160:163], v[192:195], v[44:47]
	v_mfma_f32_16x16x32_bf16 v[52:55], v[144:147], v[192:195], v[52:55]
	v_mfma_f32_16x16x32_bf16 v[36:39], v[144:147], v[200:203], v[36:39]
	v_mfma_f32_16x16x32_bf16 v[28:31], v[160:163], v[200:203], v[28:31]
	v_mfma_f32_16x16x32_bf16 v[16:19], v[168:171], v[200:203], v[16:19]
	v_mfma_f32_16x16x32_bf16 v[8:11], v[176:179], v[200:203], v[8:11]
	v_mfma_f32_16x16x32_bf16 v[0:3], v[176:179], v[208:211], v[0:3]
	v_mfma_f32_16x16x32_bf16 v[4:7], v[168:171], v[208:211], v[4:7]
	v_mfma_f32_16x16x32_bf16 v[12:15], v[160:163], v[208:211], v[12:15]
	v_mfma_f32_16x16x32_bf16 v[20:23], v[144:147], v[208:211], v[20:23]
	v_mfma_f32_16x16x32_bf16 v[20:23], v[156:159], v[212:215], v[20:23]
	v_mfma_f32_16x16x32_bf16 v[36:39], v[156:159], v[204:207], v[36:39]
	v_mfma_f32_16x16x32_bf16 v[52:55], v[156:159], v[196:199], v[52:55]
	v_mfma_f32_16x16x32_bf16 v[60:63], v[156:159], v[188:191], v[60:63]
	v_mfma_f32_16x16x32_bf16 v[56:59], v[164:167], v[188:191], v[56:59]
	v_mfma_f32_16x16x32_bf16 v[44:47], v[164:167], v[196:199], v[44:47]
	v_mfma_f32_16x16x32_bf16 v[28:31], v[164:167], v[204:207], v[28:31]
	v_mfma_f32_16x16x32_bf16 v[12:15], v[164:167], v[212:215], v[12:15]
	v_mfma_f32_16x16x32_bf16 v[4:7], v[172:175], v[212:215], v[4:7]
	v_mfma_f32_16x16x32_bf16 v[16:19], v[172:175], v[204:207], v[16:19]
	v_mfma_f32_16x16x32_bf16 v[32:35], v[172:175], v[196:199], v[32:35]
	v_mfma_f32_16x16x32_bf16 v[48:51], v[172:175], v[188:191], v[48:51]
	v_mfma_f32_16x16x32_bf16 v[40:43], v[180:183], v[188:191], v[40:43]
	v_mfma_f32_16x16x32_bf16 v[24:27], v[180:183], v[196:199], v[24:27]
	v_mfma_f32_16x16x32_bf16 v[8:11], v[180:183], v[204:207], v[8:11]
	v_mfma_f32_16x16x32_bf16 v[0:3], v[180:183], v[212:215], v[0:3]
	s_barrier
	s_add_i32 s57, 0, 0x18000
	v_add_u32_e32 v155, s57, v149
	s_add_i32 s58, 0, 0x1c000
	ds_read_b128 v[144:147], v155
	ds_read_b128 v[156:159], v155 offset:1024
	ds_read_b128 v[160:163], v155 offset:2048
	ds_read_b128 v[164:167], v155 offset:3072
	v_add_u32_e32 v155, s58, v149
	ds_read_b128 v[168:171], v155
	ds_read_b128 v[172:175], v155 offset:1024
	ds_read_b128 v[176:179], v155 offset:2048
	ds_read_b128 v[180:183], v155 offset:3072
	s_add_u32 s24, s34, 0x100000
	s_addc_u32 s25, s35, 0
	s_mov_b32 m0, s43
	v_lshl_add_u64 v[184:185], s[24:25], 0, v[128:129]
	global_load_lds_dwordx4 v[184:185], off
	v_lshl_add_u64 v[184:185], s[24:25], 0, v[132:133]
	s_mov_b32 m0, s44
	s_nop 0
	global_load_lds_dwordx4 v[184:185], off
	ds_read_b128 v[184:187], v154 offset:32768
	ds_read_b128 v[188:191], v154 offset:33792
	ds_read_b128 v[192:195], v154 offset:34816
	ds_read_b128 v[196:199], v154 offset:35840
	ds_read_b128 v[200:203], v154 offset:36864
	ds_read_b128 v[204:207], v154 offset:37888
	ds_read_b128 v[208:211], v154 offset:38912
	ds_read_b128 v[212:215], v154 offset:39936
	s_waitcnt vmcnt(8)
	s_waitcnt lgkmcnt(0)
	s_barrier
	s_waitcnt lgkmcnt(0)
	v_mfma_f32_16x16x32_bf16 v[124:127], v[144:147], v[184:187], v[124:127]
	v_mfma_f32_16x16x32_bf16 v[120:123], v[160:163], v[184:187], v[120:123]
	v_mfma_f32_16x16x32_bf16 v[112:115], v[168:171], v[184:187], v[112:115]
	v_mfma_f32_16x16x32_bf16 v[104:107], v[176:179], v[184:187], v[104:107]
	v_mfma_f32_16x16x32_bf16 v[88:91], v[176:179], v[192:195], v[88:91]
	v_mfma_f32_16x16x32_bf16 v[96:99], v[168:171], v[192:195], v[96:99]
	v_mfma_f32_16x16x32_bf16 v[108:111], v[160:163], v[192:195], v[108:111]
	v_mfma_f32_16x16x32_bf16 v[116:119], v[144:147], v[192:195], v[116:119]
	v_mfma_f32_16x16x32_bf16 v[100:103], v[144:147], v[200:203], v[100:103]
	v_mfma_f32_16x16x32_bf16 v[92:95], v[160:163], v[200:203], v[92:95]
	v_mfma_f32_16x16x32_bf16 v[80:83], v[168:171], v[200:203], v[80:83]
	v_mfma_f32_16x16x32_bf16 v[72:75], v[176:179], v[200:203], v[72:75]
	v_mfma_f32_16x16x32_bf16 v[64:67], v[176:179], v[208:211], v[64:67]
	v_mfma_f32_16x16x32_bf16 v[68:71], v[168:171], v[208:211], v[68:71]
	v_mfma_f32_16x16x32_bf16 v[76:79], v[160:163], v[208:211], v[76:79]
	v_mfma_f32_16x16x32_bf16 v[84:87], v[144:147], v[208:211], v[84:87]
	v_mfma_f32_16x16x32_bf16 v[84:87], v[156:159], v[212:215], v[84:87]
	v_mfma_f32_16x16x32_bf16 v[100:103], v[156:159], v[204:207], v[100:103]
	v_mfma_f32_16x16x32_bf16 v[116:119], v[156:159], v[196:199], v[116:119]
	v_mfma_f32_16x16x32_bf16 v[124:127], v[156:159], v[188:191], v[124:127]
	v_mfma_f32_16x16x32_bf16 v[120:123], v[164:167], v[188:191], v[120:123]
	v_mfma_f32_16x16x32_bf16 v[108:111], v[164:167], v[196:199], v[108:111]
	v_mfma_f32_16x16x32_bf16 v[92:95], v[164:167], v[204:207], v[92:95]
	v_mfma_f32_16x16x32_bf16 v[76:79], v[164:167], v[212:215], v[76:79]
	v_mfma_f32_16x16x32_bf16 v[68:71], v[172:175], v[212:215], v[68:71]
	v_mfma_f32_16x16x32_bf16 v[80:83], v[172:175], v[204:207], v[80:83]
	v_mfma_f32_16x16x32_bf16 v[96:99], v[172:175], v[196:199], v[96:99]
	v_mfma_f32_16x16x32_bf16 v[112:115], v[172:175], v[188:191], v[112:115]
	v_mfma_f32_16x16x32_bf16 v[104:107], v[180:183], v[188:191], v[104:107]
	v_mfma_f32_16x16x32_bf16 v[88:91], v[180:183], v[196:199], v[88:91]
	v_mfma_f32_16x16x32_bf16 v[72:75], v[180:183], v[204:207], v[72:75]
	v_mfma_f32_16x16x32_bf16 v[64:67], v[180:183], v[212:215], v[64:67]
	s_barrier
	s_add_i32 s24, s57, s41
	v_lshl_add_u64 v[184:185], v[216:217], 0, s[8:9]
	s_mov_b32 m0, s24
	s_nop 0
	global_load_lds_dwordx4 v[184:185], off
	s_add_i32 m0, s24, 0x2000
	s_add_u32 s24, s30, 0x100080
	v_lshl_add_u64 v[184:185], v[218:219], 0, s[8:9]
	s_addc_u32 s25, s31, 0
	s_add_i32 s30, s58, s41
	global_load_lds_dwordx4 v[184:185], off
	v_lshl_add_u64 v[184:185], s[24:25], 0, v[130:131]
	s_mov_b32 m0, s30
	s_nop 0
	global_load_lds_dwordx4 v[184:185], off
	v_lshl_add_u64 v[184:185], s[24:25], 0, v[134:135]
	s_add_i32 m0, s30, 0x2000
	s_nop 0
	global_load_lds_dwordx4 v[184:185], off
	v_lshl_add_u64 v[184:185], v[220:221], 0, s[8:9]
	s_mov_b32 m0, s46
	s_nop 0
	global_load_lds_dwordx4 v[184:185], off
	v_lshl_add_u64 v[184:185], v[222:223], 0, s[8:9]
	s_mov_b32 m0, s47
	s_nop 0
	global_load_lds_dwordx4 v[184:185], off
	ds_read_b128 v[184:187], v154 offset:49152
	ds_read_b128 v[188:191], v154 offset:50176
	ds_read_b128 v[192:195], v154 offset:51200
	ds_read_b128 v[196:199], v154 offset:52224
	ds_read_b128 v[200:203], v154 offset:53248
	ds_read_b128 v[204:207], v154 offset:54272
	ds_read_b128 v[208:211], v154 offset:55296
	ds_read_b128 v[212:215], v154 offset:56320
	s_waitcnt vmcnt(8)
	s_waitcnt lgkmcnt(0)
	s_barrier
	s_waitcnt lgkmcnt(0)
	v_mfma_f32_16x16x32_bf16 v[60:63], v[144:147], v[184:187], v[60:63]
	v_mfma_f32_16x16x32_bf16 v[56:59], v[160:163], v[184:187], v[56:59]
	v_mfma_f32_16x16x32_bf16 v[48:51], v[168:171], v[184:187], v[48:51]
	v_mfma_f32_16x16x32_bf16 v[40:43], v[176:179], v[184:187], v[40:43]
	v_mfma_f32_16x16x32_bf16 v[24:27], v[176:179], v[192:195], v[24:27]
	v_mfma_f32_16x16x32_bf16 v[32:35], v[168:171], v[192:195], v[32:35]
	v_mfma_f32_16x16x32_bf16 v[44:47], v[160:163], v[192:195], v[44:47]
	v_mfma_f32_16x16x32_bf16 v[52:55], v[144:147], v[192:195], v[52:55]
	v_mfma_f32_16x16x32_bf16 v[36:39], v[144:147], v[200:203], v[36:39]
	v_mfma_f32_16x16x32_bf16 v[28:31], v[160:163], v[200:203], v[28:31]
	v_mfma_f32_16x16x32_bf16 v[16:19], v[168:171], v[200:203], v[16:19]
	v_mfma_f32_16x16x32_bf16 v[8:11], v[176:179], v[200:203], v[8:11]
	v_mfma_f32_16x16x32_bf16 v[0:3], v[176:179], v[208:211], v[0:3]
	v_mfma_f32_16x16x32_bf16 v[4:7], v[168:171], v[208:211], v[4:7]
	v_mfma_f32_16x16x32_bf16 v[12:15], v[160:163], v[208:211], v[12:15]
	v_mfma_f32_16x16x32_bf16 v[20:23], v[144:147], v[208:211], v[20:23]
	v_mfma_f32_16x16x32_bf16 v[20:23], v[156:159], v[212:215], v[20:23]
	v_mfma_f32_16x16x32_bf16 v[36:39], v[156:159], v[204:207], v[36:39]
	v_mfma_f32_16x16x32_bf16 v[52:55], v[156:159], v[196:199], v[52:55]
	v_mfma_f32_16x16x32_bf16 v[60:63], v[156:159], v[188:191], v[60:63]
	v_mfma_f32_16x16x32_bf16 v[56:59], v[164:167], v[188:191], v[56:59]
	v_mfma_f32_16x16x32_bf16 v[44:47], v[164:167], v[196:199], v[44:47]
	v_mfma_f32_16x16x32_bf16 v[28:31], v[164:167], v[204:207], v[28:31]
	v_mfma_f32_16x16x32_bf16 v[12:15], v[164:167], v[212:215], v[12:15]
	v_mfma_f32_16x16x32_bf16 v[4:7], v[172:175], v[212:215], v[4:7]
	v_mfma_f32_16x16x32_bf16 v[16:19], v[172:175], v[204:207], v[16:19]
	v_mfma_f32_16x16x32_bf16 v[32:35], v[172:175], v[196:199], v[32:35]
	v_mfma_f32_16x16x32_bf16 v[48:51], v[172:175], v[188:191], v[48:51]
	v_mfma_f32_16x16x32_bf16 v[40:43], v[180:183], v[188:191], v[40:43]
	v_mfma_f32_16x16x32_bf16 v[24:27], v[180:183], v[196:199], v[24:27]
	v_mfma_f32_16x16x32_bf16 v[8:11], v[180:183], v[204:207], v[8:11]
	v_mfma_f32_16x16x32_bf16 v[0:3], v[180:183], v[212:215], v[0:3]
	s_barrier
	s_add_i32 s56, s56, 2
	s_add_u32 s54, s54, 0x100
	s_addc_u32 s55, s55, 0
	s_cmp_gt_u32 s56, 61
	s_mov_b64 s[24:25], s[28:29]
	s_cbranch_scc0 .LBB0_333
	s_and_b64 vcc, exec, s[0:1]
	s_cbranch_vccz .LBB0_336
	s_barrier

.LBB0_1202:
	ds_read_b128 v[128:131], v176
	ds_read_b128 v[132:135], v176 offset:1024
	ds_read_b128 v[136:139], v176 offset:2048
	ds_read_b128 v[140:143], v176 offset:3072
	ds_read_b128 v[144:147], v177
	ds_read_b128 v[148:151], v177 offset:1024
	ds_read_b128 v[180:183], v177 offset:2048
	ds_read_b128 v[184:187], v177 offset:3072
	s_add_u32 s30, s28, 0xfff00080
	s_addc_u32 s31, s29, -1
	s_cmp_eq_u32 s40, 60
	s_cselect_b32 s35, s23, s31
	s_cselect_b32 s34, s36, s30
	s_cselect_b32 s31, s21, s39
	s_cselect_b32 s30, s37, s38
	v_lshl_add_u64 v[172:173], s[28:29], 0, v[164:165]
	s_add_i32 m0, s7, 0xc000
	s_nop 0
	global_load_lds_dwordx4 v[172:173], off
	v_lshl_add_u64 v[172:173], s[28:29], 0, v[166:167]
	s_add_i32 m0, s7, 0xe000
	s_nop 0
	global_load_lds_dwordx4 v[172:173], off
	ds_read_b128 v[188:191], v178
	ds_read_b128 v[192:195], v178 offset:1024
	ds_read_b128 v[196:199], v178 offset:2048
	ds_read_b128 v[200:203], v178 offset:3072
	ds_read_b128 v[204:207], v178 offset:4096
	ds_read_b128 v[208:211], v178 offset:5120
	ds_read_b128 v[212:215], v178 offset:6144
	ds_read_b128 v[216:219], v178 offset:7168
	s_waitcnt vmcnt(8)
	s_waitcnt lgkmcnt(0)
	s_barrier
	s_waitcnt lgkmcnt(0)
	v_mfma_f32_16x16x32_bf16 v[124:127], v[128:131], v[188:191], v[124:127]
	v_mfma_f32_16x16x32_bf16 v[120:123], v[136:139], v[188:191], v[120:123]
	v_mfma_f32_16x16x32_bf16 v[116:119], v[144:147], v[188:191], v[116:119]
	v_mfma_f32_16x16x32_bf16 v[112:115], v[180:183], v[188:191], v[112:115]
	v_mfma_f32_16x16x32_bf16 v[96:99], v[180:183], v[196:199], v[96:99]
	v_mfma_f32_16x16x32_bf16 v[100:103], v[144:147], v[196:199], v[100:103]
	v_mfma_f32_16x16x32_bf16 v[104:107], v[136:139], v[196:199], v[104:107]
	v_mfma_f32_16x16x32_bf16 v[108:111], v[128:131], v[196:199], v[108:111]
	v_mfma_f32_16x16x32_bf16 v[92:95], v[128:131], v[204:207], v[92:95]
	v_mfma_f32_16x16x32_bf16 v[88:91], v[136:139], v[204:207], v[88:91]
	v_mfma_f32_16x16x32_bf16 v[84:87], v[144:147], v[204:207], v[84:87]
	v_mfma_f32_16x16x32_bf16 v[80:83], v[180:183], v[204:207], v[80:83]
	v_mfma_f32_16x16x32_bf16 v[64:67], v[180:183], v[212:215], v[64:67]
	v_mfma_f32_16x16x32_bf16 v[68:71], v[144:147], v[212:215], v[68:71]
	v_mfma_f32_16x16x32_bf16 v[72:75], v[136:139], v[212:215], v[72:75]
	v_mfma_f32_16x16x32_bf16 v[76:79], v[128:131], v[212:215], v[76:79]
	v_mfma_f32_16x16x32_bf16 v[76:79], v[132:135], v[216:219], v[76:79]
	v_mfma_f32_16x16x32_bf16 v[92:95], v[132:135], v[208:211], v[92:95]
	v_mfma_f32_16x16x32_bf16 v[108:111], v[132:135], v[200:203], v[108:111]
	v_mfma_f32_16x16x32_bf16 v[124:127], v[132:135], v[192:195], v[124:127]
	v_mfma_f32_16x16x32_bf16 v[120:123], v[140:143], v[192:195], v[120:123]
	v_mfma_f32_16x16x32_bf16 v[104:107], v[140:143], v[200:203], v[104:107]
	v_mfma_f32_16x16x32_bf16 v[88:91], v[140:143], v[208:211], v[88:91]
	v_mfma_f32_16x16x32_bf16 v[72:75], v[140:143], v[216:219], v[72:75]
	v_mfma_f32_16x16x32_bf16 v[68:71], v[148:151], v[216:219], v[68:71]
	v_mfma_f32_16x16x32_bf16 v[84:87], v[148:151], v[208:211], v[84:87]
	v_mfma_f32_16x16x32_bf16 v[100:103], v[148:151], v[200:203], v[100:103]
	v_mfma_f32_16x16x32_bf16 v[116:119], v[148:151], v[192:195], v[116:119]
	v_mfma_f32_16x16x32_bf16 v[112:115], v[184:187], v[192:195], v[112:115]
	v_mfma_f32_16x16x32_bf16 v[96:99], v[184:187], v[200:203], v[96:99]
	v_mfma_f32_16x16x32_bf16 v[80:83], v[184:187], v[208:211], v[80:83]
	v_mfma_f32_16x16x32_bf16 v[64:67], v[184:187], v[216:219], v[64:67]
	s_barrier
	s_add_i32 s41, s68, s33
	v_lshl_add_u64 v[172:173], s[30:31], 0, v[154:155]
	s_mov_b32 m0, s41
	v_lshl_add_u64 v[220:221], s[30:31], 0, v[158:159]
	global_load_lds_dwordx4 v[172:173], off
	s_add_i32 m0, s41, 0x2000
	s_add_u32 s42, s30, 0x100000
	s_addc_u32 s43, s31, 0
	s_add_i32 s41, s69, s33
	global_load_lds_dwordx4 v[220:221], off
	v_lshl_add_u64 v[188:189], s[42:43], 0, v[154:155]
	s_mov_b32 m0, s41
	v_lshl_add_u64 v[222:223], s[34:35], 0, v[152:153]
	global_load_lds_dwordx4 v[188:189], off
	v_lshl_add_u64 v[188:189], s[42:43], 0, v[158:159]
	s_add_i32 m0, s41, 0x2000
	v_lshl_add_u64 v[224:225], s[34:35], 0, v[156:157]
	global_load_lds_dwordx4 v[188:189], off
	s_mov_b32 m0, s7
	s_nop 0
	global_load_lds_dwordx4 v[222:223], off
	s_mov_b32 m0, s59
	s_nop 0
	global_load_lds_dwordx4 v[224:225], off
	ds_read_b128 v[188:191], v178 offset:16384
	ds_read_b128 v[192:195], v178 offset:17408
	ds_read_b128 v[196:199], v178 offset:18432
	ds_read_b128 v[200:203], v178 offset:19456
	ds_read_b128 v[204:207], v178 offset:20480
	ds_read_b128 v[208:211], v178 offset:21504
	ds_read_b128 v[212:215], v178 offset:22528
	ds_read_b128 v[216:219], v178 offset:23552
	s_waitcnt vmcnt(8)
	s_waitcnt lgkmcnt(0)
	s_barrier
	s_waitcnt lgkmcnt(0)
	v_mfma_f32_16x16x32_bf16 v[60:63], v[128:131], v[188:191], v[60:63]
	v_mfma_f32_16x16x32_bf16 v[56:59], v[136:139], v[188:191], v[56:59]
	v_mfma_f32_16x16x32_bf16 v[52:55], v[144:147], v[188:191], v[52:55]
	v_mfma_f32_16x16x32_bf16 v[48:51], v[180:183], v[188:191], v[48:51]
	v_mfma_f32_16x16x32_bf16 v[32:35], v[180:183], v[196:199], v[32:35]
	v_mfma_f32_16x16x32_bf16 v[36:39], v[144:147], v[196:199], v[36:39]
	v_mfma_f32_16x16x32_bf16 v[40:43], v[136:139], v[196:199], v[40:43]
	v_mfma_f32_16x16x32_bf16 v[44:47], v[128:131], v[196:199], v[44:47]
	v_mfma_f32_16x16x32_bf16 v[28:31], v[128:131], v[204:207], v[28:31]
	v_mfma_f32_16x16x32_bf16 v[24:27], v[136:139], v[204:207], v[24:27]
	v_mfma_f32_16x16x32_bf16 v[20:23], v[144:147], v[204:207], v[20:23]
	v_mfma_f32_16x16x32_bf16 v[16:19], v[180:183], v[204:207], v[16:19]
	v_mfma_f32_16x16x32_bf16 v[0:3], v[180:183], v[212:215], v[0:3]
	v_mfma_f32_16x16x32_bf16 v[4:7], v[144:147], v[212:215], v[4:7]
	v_mfma_f32_16x16x32_bf16 v[8:11], v[136:139], v[212:215], v[8:11]
	v_mfma_f32_16x16x32_bf16 v[12:15], v[128:131], v[212:215], v[12:15]
	v_mfma_f32_16x16x32_bf16 v[12:15], v[132:135], v[216:219], v[12:15]
	v_mfma_f32_16x16x32_bf16 v[28:31], v[132:135], v[208:211], v[28:31]
	v_mfma_f32_16x16x32_bf16 v[44:47], v[132:135], v[200:203], v[44:47]
	v_mfma_f32_16x16x32_bf16 v[60:63], v[132:135], v[192:195], v[60:63]
	v_mfma_f32_16x16x32_bf16 v[56:59], v[140:143], v[192:195], v[56:59]
	v_mfma_f32_16x16x32_bf16 v[40:43], v[140:143], v[200:203], v[40:43]
	v_mfma_f32_16x16x32_bf16 v[24:27], v[140:143], v[208:211], v[24:27]
	v_mfma_f32_16x16x32_bf16 v[8:11], v[140:143], v[216:219], v[8:11]
	v_mfma_f32_16x16x32_bf16 v[4:7], v[148:151], v[216:219], v[4:7]
	v_mfma_f32_16x16x32_bf16 v[20:23], v[148:151], v[208:211], v[20:23]
	v_mfma_f32_16x16x32_bf16 v[36:39], v[148:151], v[200:203], v[36:39]
	v_mfma_f32_16x16x32_bf16 v[52:55], v[148:151], v[192:195], v[52:55]
	v_mfma_f32_16x16x32_bf16 v[48:51], v[184:187], v[192:195], v[48:51]
	v_mfma_f32_16x16x32_bf16 v[32:35], v[184:187], v[200:203], v[32:35]
	v_mfma_f32_16x16x32_bf16 v[16:19], v[184:187], v[208:211], v[16:19]
	v_mfma_f32_16x16x32_bf16 v[0:3], v[184:187], v[216:219], v[0:3]
	s_barrier
	s_add_i32 s41, 0, 0x18000
	s_add_i32 s42, 0, 0x1c000
	v_add_u32_e32 v140, s41, v174
	v_add_u32_e32 v184, s42, v174
	ds_read_b128 v[128:131], v140
	ds_read_b128 v[132:135], v140 offset:1024
	ds_read_b128 v[136:139], v140 offset:2048
	ds_read_b128 v[140:143], v140 offset:3072
	ds_read_b128 v[144:147], v184
	ds_read_b128 v[148:151], v184 offset:1024
	ds_read_b128 v[180:183], v184 offset:2048
	ds_read_b128 v[184:187], v184 offset:3072
	s_add_u32 s34, s34, 0x100000
	s_addc_u32 s35, s35, 0
	s_mov_b32 m0, s60
	v_lshl_add_u64 v[188:189], s[34:35], 0, v[152:153]
	global_load_lds_dwordx4 v[188:189], off
	v_lshl_add_u64 v[188:189], s[34:35], 0, v[156:157]
	s_mov_b32 m0, s61
	s_nop 0
	global_load_lds_dwordx4 v[188:189], off
	ds_read_b128 v[188:191], v178 offset:32768
	ds_read_b128 v[192:195], v178 offset:33792
	ds_read_b128 v[196:199], v178 offset:34816
	ds_read_b128 v[200:203], v178 offset:35840
	ds_read_b128 v[204:207], v178 offset:36864
	ds_read_b128 v[208:211], v178 offset:37888
	ds_read_b128 v[212:215], v178 offset:38912
	ds_read_b128 v[216:219], v178 offset:39936
	s_waitcnt vmcnt(8)
	s_waitcnt lgkmcnt(0)
	s_barrier
	s_waitcnt lgkmcnt(0)
	v_mfma_f32_16x16x32_bf16 v[124:127], v[128:131], v[188:191], v[124:127]
	v_mfma_f32_16x16x32_bf16 v[120:123], v[136:139], v[188:191], v[120:123]
	v_mfma_f32_16x16x32_bf16 v[116:119], v[144:147], v[188:191], v[116:119]
	v_mfma_f32_16x16x32_bf16 v[112:115], v[180:183], v[188:191], v[112:115]
	v_mfma_f32_16x16x32_bf16 v[96:99], v[180:183], v[196:199], v[96:99]
	v_mfma_f32_16x16x32_bf16 v[100:103], v[144:147], v[196:199], v[100:103]
	v_mfma_f32_16x16x32_bf16 v[104:107], v[136:139], v[196:199], v[104:107]
	v_mfma_f32_16x16x32_bf16 v[108:111], v[128:131], v[196:199], v[108:111]
	v_mfma_f32_16x16x32_bf16 v[92:95], v[128:131], v[204:207], v[92:95]
	v_mfma_f32_16x16x32_bf16 v[88:91], v[136:139], v[204:207], v[88:91]
	v_mfma_f32_16x16x32_bf16 v[84:87], v[144:147], v[204:207], v[84:87]
	v_mfma_f32_16x16x32_bf16 v[80:83], v[180:183], v[204:207], v[80:83]
	v_mfma_f32_16x16x32_bf16 v[64:67], v[180:183], v[212:215], v[64:67]
	v_mfma_f32_16x16x32_bf16 v[68:71], v[144:147], v[212:215], v[68:71]
	v_mfma_f32_16x16x32_bf16 v[72:75], v[136:139], v[212:215], v[72:75]
	v_mfma_f32_16x16x32_bf16 v[76:79], v[128:131], v[212:215], v[76:79]
	v_mfma_f32_16x16x32_bf16 v[76:79], v[132:135], v[216:219], v[76:79]
	v_mfma_f32_16x16x32_bf16 v[92:95], v[132:135], v[208:211], v[92:95]
	v_mfma_f32_16x16x32_bf16 v[108:111], v[132:135], v[200:203], v[108:111]
	v_mfma_f32_16x16x32_bf16 v[124:127], v[132:135], v[192:195], v[124:127]
	v_mfma_f32_16x16x32_bf16 v[120:123], v[140:143], v[192:195], v[120:123]
	v_mfma_f32_16x16x32_bf16 v[104:107], v[140:143], v[200:203], v[104:107]
	v_mfma_f32_16x16x32_bf16 v[88:91], v[140:143], v[208:211], v[88:91]
	v_mfma_f32_16x16x32_bf16 v[72:75], v[140:143], v[216:219], v[72:75]
	v_mfma_f32_16x16x32_bf16 v[68:71], v[148:151], v[216:219], v[68:71]
	v_mfma_f32_16x16x32_bf16 v[84:87], v[148:151], v[208:211], v[84:87]
	v_mfma_f32_16x16x32_bf16 v[100:103], v[148:151], v[200:203], v[100:103]
	v_mfma_f32_16x16x32_bf16 v[116:119], v[148:151], v[192:195], v[116:119]
	v_mfma_f32_16x16x32_bf16 v[112:115], v[184:187], v[192:195], v[112:115]
	v_mfma_f32_16x16x32_bf16 v[96:99], v[184:187], v[200:203], v[96:99]
	v_mfma_f32_16x16x32_bf16 v[80:83], v[184:187], v[208:211], v[80:83]
	v_mfma_f32_16x16x32_bf16 v[64:67], v[184:187], v[216:219], v[64:67]
	s_barrier
	s_add_i32 s34, s41, s33
	v_lshl_add_u64 v[172:173], v[172:173], 0, s[16:17]
	s_mov_b32 m0, s34
	s_nop 0
	global_load_lds_dwordx4 v[172:173], off
	s_add_i32 m0, s34, 0x2000
	s_add_u32 s30, s30, 0x100800
	v_lshl_add_u64 v[172:173], v[220:221], 0, s[16:17]
	s_addc_u32 s31, s31, 0
	s_add_i32 s34, s42, s33
	global_load_lds_dwordx4 v[172:173], off
	v_lshl_add_u64 v[172:173], s[30:31], 0, v[154:155]
	s_mov_b32 m0, s34
	s_nop 0
	global_load_lds_dwordx4 v[172:173], off
	v_lshl_add_u64 v[172:173], s[30:31], 0, v[158:159]
	s_add_i32 m0, s34, 0x2000
	s_nop 0
	global_load_lds_dwordx4 v[172:173], off
	v_lshl_add_u64 v[172:173], v[222:223], 0, s[18:19]
	s_mov_b32 m0, s63
	s_nop 0
	global_load_lds_dwordx4 v[172:173], off
	v_lshl_add_u64 v[172:173], v[224:225], 0, s[18:19]
	s_mov_b32 m0, s64
	s_nop 0
	global_load_lds_dwordx4 v[172:173], off
	ds_read_b128 v[188:191], v178 offset:49152
	ds_read_b128 v[192:195], v178 offset:50176
	ds_read_b128 v[196:199], v178 offset:51200
	ds_read_b128 v[200:203], v178 offset:52224
	ds_read_b128 v[204:207], v178 offset:53248
	ds_read_b128 v[208:211], v178 offset:54272
	ds_read_b128 v[212:215], v178 offset:55296
	ds_read_b128 v[216:219], v178 offset:56320
	s_waitcnt vmcnt(8)
	s_waitcnt lgkmcnt(0)
	s_barrier
	s_waitcnt lgkmcnt(0)
	v_mfma_f32_16x16x32_bf16 v[60:63], v[128:131], v[188:191], v[60:63]
	v_mfma_f32_16x16x32_bf16 v[56:59], v[136:139], v[188:191], v[56:59]
	v_mfma_f32_16x16x32_bf16 v[52:55], v[144:147], v[188:191], v[52:55]
	v_mfma_f32_16x16x32_bf16 v[48:51], v[180:183], v[188:191], v[48:51]
	v_mfma_f32_16x16x32_bf16 v[32:35], v[180:183], v[196:199], v[32:35]
	v_mfma_f32_16x16x32_bf16 v[36:39], v[144:147], v[196:199], v[36:39]
	v_mfma_f32_16x16x32_bf16 v[40:43], v[136:139], v[196:199], v[40:43]
	v_mfma_f32_16x16x32_bf16 v[44:47], v[128:131], v[196:199], v[44:47]
	v_mfma_f32_16x16x32_bf16 v[28:31], v[128:131], v[204:207], v[28:31]
	v_mfma_f32_16x16x32_bf16 v[24:27], v[136:139], v[204:207], v[24:27]
	v_mfma_f32_16x16x32_bf16 v[20:23], v[144:147], v[204:207], v[20:23]
	v_mfma_f32_16x16x32_bf16 v[16:19], v[180:183], v[204:207], v[16:19]
	v_mfma_f32_16x16x32_bf16 v[0:3], v[180:183], v[212:215], v[0:3]
	v_mfma_f32_16x16x32_bf16 v[4:7], v[144:147], v[212:215], v[4:7]
	v_mfma_f32_16x16x32_bf16 v[8:11], v[136:139], v[212:215], v[8:11]
	v_mfma_f32_16x16x32_bf16 v[12:15], v[128:131], v[212:215], v[12:15]
	v_mfma_f32_16x16x32_bf16 v[12:15], v[132:135], v[216:219], v[12:15]
	v_mfma_f32_16x16x32_bf16 v[28:31], v[132:135], v[208:211], v[28:31]
	v_mfma_f32_16x16x32_bf16 v[44:47], v[132:135], v[200:203], v[44:47]
	v_mfma_f32_16x16x32_bf16 v[60:63], v[132:135], v[192:195], v[60:63]
	v_mfma_f32_16x16x32_bf16 v[56:59], v[140:143], v[192:195], v[56:59]
	v_mfma_f32_16x16x32_bf16 v[40:43], v[140:143], v[200:203], v[40:43]
	v_mfma_f32_16x16x32_bf16 v[24:27], v[140:143], v[208:211], v[24:27]
	v_mfma_f32_16x16x32_bf16 v[8:11], v[140:143], v[216:219], v[8:11]
	v_mfma_f32_16x16x32_bf16 v[4:7], v[148:151], v[216:219], v[4:7]
	v_mfma_f32_16x16x32_bf16 v[20:23], v[148:151], v[208:211], v[20:23]
	v_mfma_f32_16x16x32_bf16 v[36:39], v[148:151], v[200:203], v[36:39]
	v_mfma_f32_16x16x32_bf16 v[52:55], v[148:151], v[192:195], v[52:55]
	v_mfma_f32_16x16x32_bf16 v[48:51], v[184:187], v[192:195], v[48:51]
	v_mfma_f32_16x16x32_bf16 v[32:35], v[184:187], v[200:203], v[32:35]
	v_mfma_f32_16x16x32_bf16 v[16:19], v[184:187], v[208:211], v[16:19]
	v_mfma_f32_16x16x32_bf16 v[0:3], v[184:187], v[216:219], v[0:3]
	s_barrier
	s_add_i32 s40, s40, 2
	s_add_u32 s38, s38, 0x1000
	s_addc_u32 s39, s39, 0
	s_add_u32 s28, s28, 0x100
	s_addc_u32 s29, s29, 0
	s_cmp_gt_u32 s40, 61
	s_cbranch_scc0 .LBB0_1202
	s_and_b64 vcc, exec, s[10:11]
	s_cbranch_vccz .LBB0_1205
	s_barrier

.LBB0_1263:
	ds_read_b128 v[146:149], v152
	ds_read_b128 v[156:159], v152 offset:1024
	ds_read_b128 v[160:163], v152 offset:2048
	ds_read_b128 v[164:167], v152 offset:3072
	ds_read_b128 v[168:171], v153
	ds_read_b128 v[172:175], v153 offset:1024
	ds_read_b128 v[176:179], v153 offset:2048
	ds_read_b128 v[180:183], v153 offset:3072
	s_add_u32 s22, s20, 0x100
	s_addc_u32 s23, s21, 0
	s_cmp_eq_u32 s46, 12
	s_cselect_b32 s27, s5, s23
	s_cselect_b32 s26, s4, s22
	s_cselect_b32 s25, s19, s15
	s_cselect_b32 s24, s18, s6
	v_lshl_add_u64 v[184:185], s[20:21], 0, v[136:137]
	s_add_i32 m0, s17, 0xc000
	s_nop 0
	global_load_lds_dwordx4 v[184:185], off
	v_lshl_add_u64 v[184:185], s[20:21], 0, v[138:139]
	s_add_i32 m0, s17, 0xe000
	s_nop 0
	global_load_lds_dwordx4 v[184:185], off
	ds_read_b128 v[184:187], v154
	ds_read_b128 v[188:191], v154 offset:1024
	ds_read_b128 v[192:195], v154 offset:2048
	ds_read_b128 v[196:199], v154 offset:3072
	ds_read_b128 v[200:203], v154 offset:4096
	ds_read_b128 v[204:207], v154 offset:5120
	ds_read_b128 v[208:211], v154 offset:6144
	ds_read_b128 v[212:215], v154 offset:7168
	s_waitcnt vmcnt(8)
	s_waitcnt lgkmcnt(0)
	s_barrier
	s_waitcnt lgkmcnt(0)
	v_mfma_f32_16x16x32_bf16 v[124:127], v[146:149], v[184:187], v[124:127]
	v_mfma_f32_16x16x32_bf16 v[120:123], v[160:163], v[184:187], v[120:123]
	v_mfma_f32_16x16x32_bf16 v[116:119], v[168:171], v[184:187], v[116:119]
	v_mfma_f32_16x16x32_bf16 v[108:111], v[176:179], v[184:187], v[108:111]
	v_mfma_f32_16x16x32_bf16 v[92:95], v[176:179], v[192:195], v[92:95]
	v_mfma_f32_16x16x32_bf16 v[100:103], v[168:171], v[192:195], v[100:103]
	v_mfma_f32_16x16x32_bf16 v[104:107], v[160:163], v[192:195], v[104:107]
	v_mfma_f32_16x16x32_bf16 v[112:115], v[146:149], v[192:195], v[112:115]
	v_mfma_f32_16x16x32_bf16 v[96:99], v[146:149], v[200:203], v[96:99]
	v_mfma_f32_16x16x32_bf16 v[88:91], v[160:163], v[200:203], v[88:91]
	v_mfma_f32_16x16x32_bf16 v[84:87], v[168:171], v[200:203], v[84:87]
	v_mfma_f32_16x16x32_bf16 v[76:79], v[176:179], v[200:203], v[76:79]
	v_mfma_f32_16x16x32_bf16 v[64:67], v[176:179], v[208:211], v[64:67]
	v_mfma_f32_16x16x32_bf16 v[68:71], v[168:171], v[208:211], v[68:71]
	v_mfma_f32_16x16x32_bf16 v[72:75], v[160:163], v[208:211], v[72:75]
	v_mfma_f32_16x16x32_bf16 v[80:83], v[146:149], v[208:211], v[80:83]
	v_mfma_f32_16x16x32_bf16 v[80:83], v[156:159], v[212:215], v[80:83]
	v_mfma_f32_16x16x32_bf16 v[96:99], v[156:159], v[204:207], v[96:99]
	v_mfma_f32_16x16x32_bf16 v[112:115], v[156:159], v[196:199], v[112:115]
	v_mfma_f32_16x16x32_bf16 v[124:127], v[156:159], v[188:191], v[124:127]
	v_mfma_f32_16x16x32_bf16 v[120:123], v[164:167], v[188:191], v[120:123]
	v_mfma_f32_16x16x32_bf16 v[104:107], v[164:167], v[196:199], v[104:107]
	v_mfma_f32_16x16x32_bf16 v[88:91], v[164:167], v[204:207], v[88:91]
	v_mfma_f32_16x16x32_bf16 v[72:75], v[164:167], v[212:215], v[72:75]
	v_mfma_f32_16x16x32_bf16 v[68:71], v[172:175], v[212:215], v[68:71]
	v_mfma_f32_16x16x32_bf16 v[84:87], v[172:175], v[204:207], v[84:87]
	v_mfma_f32_16x16x32_bf16 v[100:103], v[172:175], v[196:199], v[100:103]
	v_mfma_f32_16x16x32_bf16 v[116:119], v[172:175], v[188:191], v[116:119]
	v_mfma_f32_16x16x32_bf16 v[108:111], v[180:183], v[188:191], v[108:111]
	v_mfma_f32_16x16x32_bf16 v[92:95], v[180:183], v[196:199], v[92:95]
	v_mfma_f32_16x16x32_bf16 v[76:79], v[180:183], v[204:207], v[76:79]
	v_mfma_f32_16x16x32_bf16 v[64:67], v[180:183], v[212:215], v[64:67]
	s_barrier
	s_add_i32 s20, s41, s33
	v_lshl_add_u64 v[216:217], s[24:25], 0, v[130:131]
	s_mov_b32 m0, s20
	v_lshl_add_u64 v[218:219], s[24:25], 0, v[134:135]
	global_load_lds_dwordx4 v[216:217], off
	s_add_i32 m0, s20, 0x2000
	s_add_u32 s20, s24, 0x200000
	s_addc_u32 s21, s25, 0
	s_add_i32 s47, s42, s33
	global_load_lds_dwordx4 v[218:219], off
	v_lshl_add_u64 v[184:185], s[20:21], 0, v[130:131]
	s_mov_b32 m0, s47
	v_lshl_add_u64 v[220:221], s[26:27], 0, v[128:129]
	global_load_lds_dwordx4 v[184:185], off
	v_lshl_add_u64 v[184:185], s[20:21], 0, v[134:135]
	s_add_i32 m0, s47, 0x2000
	v_lshl_add_u64 v[222:223], s[26:27], 0, v[132:133]
	global_load_lds_dwordx4 v[184:185], off
	s_mov_b32 m0, s17
	s_nop 0
	global_load_lds_dwordx4 v[220:221], off
	s_mov_b32 m0, s34
	s_nop 0
	global_load_lds_dwordx4 v[222:223], off
	ds_read_b128 v[184:187], v154 offset:16384
	ds_read_b128 v[188:191], v154 offset:17408
	ds_read_b128 v[192:195], v154 offset:18432
	ds_read_b128 v[196:199], v154 offset:19456
	ds_read_b128 v[200:203], v154 offset:20480
	ds_read_b128 v[204:207], v154 offset:21504
	ds_read_b128 v[208:211], v154 offset:22528
	ds_read_b128 v[212:215], v154 offset:23552
	s_waitcnt vmcnt(8)
	s_waitcnt lgkmcnt(0)
	s_barrier
	s_waitcnt lgkmcnt(0)
	v_mfma_f32_16x16x32_bf16 v[60:63], v[146:149], v[184:187], v[60:63]
	v_mfma_f32_16x16x32_bf16 v[56:59], v[160:163], v[184:187], v[56:59]
	v_mfma_f32_16x16x32_bf16 v[52:55], v[168:171], v[184:187], v[52:55]
	v_mfma_f32_16x16x32_bf16 v[44:47], v[176:179], v[184:187], v[44:47]
	v_mfma_f32_16x16x32_bf16 v[28:31], v[176:179], v[192:195], v[28:31]
	v_mfma_f32_16x16x32_bf16 v[36:39], v[168:171], v[192:195], v[36:39]
	v_mfma_f32_16x16x32_bf16 v[40:43], v[160:163], v[192:195], v[40:43]
	v_mfma_f32_16x16x32_bf16 v[48:51], v[146:149], v[192:195], v[48:51]
	v_mfma_f32_16x16x32_bf16 v[32:35], v[146:149], v[200:203], v[32:35]
	v_mfma_f32_16x16x32_bf16 v[24:27], v[160:163], v[200:203], v[24:27]
	v_mfma_f32_16x16x32_bf16 v[20:23], v[168:171], v[200:203], v[20:23]
	v_mfma_f32_16x16x32_bf16 v[12:15], v[176:179], v[200:203], v[12:15]
	v_mfma_f32_16x16x32_bf16 v[0:3], v[176:179], v[208:211], v[0:3]
	v_mfma_f32_16x16x32_bf16 v[4:7], v[168:171], v[208:211], v[4:7]
	v_mfma_f32_16x16x32_bf16 v[8:11], v[160:163], v[208:211], v[8:11]
	v_mfma_f32_16x16x32_bf16 v[16:19], v[146:149], v[208:211], v[16:19]
	v_mfma_f32_16x16x32_bf16 v[16:19], v[156:159], v[212:215], v[16:19]
	v_mfma_f32_16x16x32_bf16 v[32:35], v[156:159], v[204:207], v[32:35]
	v_mfma_f32_16x16x32_bf16 v[48:51], v[156:159], v[196:199], v[48:51]
	v_mfma_f32_16x16x32_bf16 v[60:63], v[156:159], v[188:191], v[60:63]
	v_mfma_f32_16x16x32_bf16 v[56:59], v[164:167], v[188:191], v[56:59]
	v_mfma_f32_16x16x32_bf16 v[40:43], v[164:167], v[196:199], v[40:43]
	v_mfma_f32_16x16x32_bf16 v[24:27], v[164:167], v[204:207], v[24:27]
	v_mfma_f32_16x16x32_bf16 v[8:11], v[164:167], v[212:215], v[8:11]
	v_mfma_f32_16x16x32_bf16 v[4:7], v[172:175], v[212:215], v[4:7]
	v_mfma_f32_16x16x32_bf16 v[20:23], v[172:175], v[204:207], v[20:23]
	v_mfma_f32_16x16x32_bf16 v[36:39], v[172:175], v[196:199], v[36:39]
	v_mfma_f32_16x16x32_bf16 v[52:55], v[172:175], v[188:191], v[52:55]
	v_mfma_f32_16x16x32_bf16 v[44:47], v[180:183], v[188:191], v[44:47]
	v_mfma_f32_16x16x32_bf16 v[28:31], v[180:183], v[196:199], v[28:31]
	v_mfma_f32_16x16x32_bf16 v[12:15], v[180:183], v[204:207], v[12:15]
	v_mfma_f32_16x16x32_bf16 v[0:3], v[180:183], v[212:215], v[0:3]
	s_barrier
	s_add_i32 s47, 0, 0x18000
	v_add_u32_e32 v144, s47, v145
	s_add_i32 s48, 0, 0x1c000
	ds_read_b128 v[146:149], v144
	ds_read_b128 v[156:159], v144 offset:1024
	ds_read_b128 v[160:163], v144 offset:2048
	ds_read_b128 v[164:167], v144 offset:3072
	v_add_u32_e32 v144, s48, v145
	ds_read_b128 v[168:171], v144
	ds_read_b128 v[172:175], v144 offset:1024
	ds_read_b128 v[176:179], v144 offset:2048
	ds_read_b128 v[180:183], v144 offset:3072
	s_add_u32 s20, s26, 0x200000
	s_addc_u32 s21, s27, 0
	s_mov_b32 m0, s35
	v_lshl_add_u64 v[184:185], s[20:21], 0, v[128:129]
	global_load_lds_dwordx4 v[184:185], off
	v_lshl_add_u64 v[184:185], s[20:21], 0, v[132:133]
	s_mov_b32 m0, s36
	s_nop 0
	global_load_lds_dwordx4 v[184:185], off
	ds_read_b128 v[184:187], v154 offset:32768
	ds_read_b128 v[188:191], v154 offset:33792
	ds_read_b128 v[192:195], v154 offset:34816
	ds_read_b128 v[196:199], v154 offset:35840
	ds_read_b128 v[200:203], v154 offset:36864
	ds_read_b128 v[204:207], v154 offset:37888
	ds_read_b128 v[208:211], v154 offset:38912
	ds_read_b128 v[212:215], v154 offset:39936
	s_waitcnt vmcnt(8)
	s_waitcnt lgkmcnt(0)
	s_barrier
	s_waitcnt lgkmcnt(0)
	v_mfma_f32_16x16x32_bf16 v[124:127], v[146:149], v[184:187], v[124:127]
	v_mfma_f32_16x16x32_bf16 v[120:123], v[160:163], v[184:187], v[120:123]
	v_mfma_f32_16x16x32_bf16 v[116:119], v[168:171], v[184:187], v[116:119]
	v_mfma_f32_16x16x32_bf16 v[108:111], v[176:179], v[184:187], v[108:111]
	v_mfma_f32_16x16x32_bf16 v[92:95], v[176:179], v[192:195], v[92:95]
	v_mfma_f32_16x16x32_bf16 v[100:103], v[168:171], v[192:195], v[100:103]
	v_mfma_f32_16x16x32_bf16 v[104:107], v[160:163], v[192:195], v[104:107]
	v_mfma_f32_16x16x32_bf16 v[112:115], v[146:149], v[192:195], v[112:115]
	v_mfma_f32_16x16x32_bf16 v[96:99], v[146:149], v[200:203], v[96:99]
	v_mfma_f32_16x16x32_bf16 v[88:91], v[160:163], v[200:203], v[88:91]
	v_mfma_f32_16x16x32_bf16 v[84:87], v[168:171], v[200:203], v[84:87]
	v_mfma_f32_16x16x32_bf16 v[76:79], v[176:179], v[200:203], v[76:79]
	v_mfma_f32_16x16x32_bf16 v[64:67], v[176:179], v[208:211], v[64:67]
	v_mfma_f32_16x16x32_bf16 v[68:71], v[168:171], v[208:211], v[68:71]
	v_mfma_f32_16x16x32_bf16 v[72:75], v[160:163], v[208:211], v[72:75]
	v_mfma_f32_16x16x32_bf16 v[80:83], v[146:149], v[208:211], v[80:83]
	v_mfma_f32_16x16x32_bf16 v[80:83], v[156:159], v[212:215], v[80:83]
	v_mfma_f32_16x16x32_bf16 v[96:99], v[156:159], v[204:207], v[96:99]
	v_mfma_f32_16x16x32_bf16 v[112:115], v[156:159], v[196:199], v[112:115]
	v_mfma_f32_16x16x32_bf16 v[124:127], v[156:159], v[188:191], v[124:127]
	v_mfma_f32_16x16x32_bf16 v[120:123], v[164:167], v[188:191], v[120:123]
	v_mfma_f32_16x16x32_bf16 v[104:107], v[164:167], v[196:199], v[104:107]
	v_mfma_f32_16x16x32_bf16 v[88:91], v[164:167], v[204:207], v[88:91]
	v_mfma_f32_16x16x32_bf16 v[72:75], v[164:167], v[212:215], v[72:75]
	v_mfma_f32_16x16x32_bf16 v[68:71], v[172:175], v[212:215], v[68:71]
	v_mfma_f32_16x16x32_bf16 v[84:87], v[172:175], v[204:207], v[84:87]
	v_mfma_f32_16x16x32_bf16 v[100:103], v[172:175], v[196:199], v[100:103]
	v_mfma_f32_16x16x32_bf16 v[116:119], v[172:175], v[188:191], v[116:119]
	v_mfma_f32_16x16x32_bf16 v[108:111], v[180:183], v[188:191], v[108:111]
	v_mfma_f32_16x16x32_bf16 v[92:95], v[180:183], v[196:199], v[92:95]
	v_mfma_f32_16x16x32_bf16 v[76:79], v[180:183], v[204:207], v[76:79]
	v_mfma_f32_16x16x32_bf16 v[64:67], v[180:183], v[212:215], v[64:67]
	s_barrier
	s_add_i32 s20, s47, s33
	v_lshl_add_u64 v[184:185], v[216:217], 0, s[12:13]
	s_mov_b32 m0, s20
	s_nop 0
	global_load_lds_dwordx4 v[184:185], off
	s_add_i32 m0, s20, 0x2000
	s_add_u32 s20, s24, 0x200080
	v_lshl_add_u64 v[184:185], v[218:219], 0, s[12:13]
	s_addc_u32 s21, s25, 0
	s_add_i32 s24, s48, s33
	global_load_lds_dwordx4 v[184:185], off
	v_lshl_add_u64 v[184:185], s[20:21], 0, v[130:131]
	s_mov_b32 m0, s24
	s_nop 0
	global_load_lds_dwordx4 v[184:185], off
	v_lshl_add_u64 v[184:185], s[20:21], 0, v[134:135]
	s_add_i32 m0, s24, 0x2000
	s_nop 0
	global_load_lds_dwordx4 v[184:185], off
	v_lshl_add_u64 v[184:185], v[220:221], 0, s[12:13]
	s_mov_b32 m0, s37
	s_nop 0
	global_load_lds_dwordx4 v[184:185], off
	v_lshl_add_u64 v[184:185], v[222:223], 0, s[12:13]
	s_mov_b32 m0, s38
	s_nop 0
	global_load_lds_dwordx4 v[184:185], off
	ds_read_b128 v[184:187], v154 offset:49152
	ds_read_b128 v[188:191], v154 offset:50176
	ds_read_b128 v[192:195], v154 offset:51200
	ds_read_b128 v[196:199], v154 offset:52224
	ds_read_b128 v[200:203], v154 offset:53248
	ds_read_b128 v[204:207], v154 offset:54272
	ds_read_b128 v[208:211], v154 offset:55296
	ds_read_b128 v[212:215], v154 offset:56320
	s_waitcnt vmcnt(8)
	s_waitcnt lgkmcnt(0)
	s_barrier
	s_waitcnt lgkmcnt(0)
	v_mfma_f32_16x16x32_bf16 v[60:63], v[146:149], v[184:187], v[60:63]
	v_mfma_f32_16x16x32_bf16 v[56:59], v[160:163], v[184:187], v[56:59]
	v_mfma_f32_16x16x32_bf16 v[52:55], v[168:171], v[184:187], v[52:55]
	v_mfma_f32_16x16x32_bf16 v[44:47], v[176:179], v[184:187], v[44:47]
	v_mfma_f32_16x16x32_bf16 v[28:31], v[176:179], v[192:195], v[28:31]
	v_mfma_f32_16x16x32_bf16 v[36:39], v[168:171], v[192:195], v[36:39]
	v_mfma_f32_16x16x32_bf16 v[40:43], v[160:163], v[192:195], v[40:43]
	v_mfma_f32_16x16x32_bf16 v[48:51], v[146:149], v[192:195], v[48:51]
	v_mfma_f32_16x16x32_bf16 v[32:35], v[146:149], v[200:203], v[32:35]
	v_mfma_f32_16x16x32_bf16 v[24:27], v[160:163], v[200:203], v[24:27]
	v_mfma_f32_16x16x32_bf16 v[20:23], v[168:171], v[200:203], v[20:23]
	v_mfma_f32_16x16x32_bf16 v[12:15], v[176:179], v[200:203], v[12:15]
	v_mfma_f32_16x16x32_bf16 v[0:3], v[176:179], v[208:211], v[0:3]
	v_mfma_f32_16x16x32_bf16 v[4:7], v[168:171], v[208:211], v[4:7]
	v_mfma_f32_16x16x32_bf16 v[8:11], v[160:163], v[208:211], v[8:11]
	v_mfma_f32_16x16x32_bf16 v[16:19], v[146:149], v[208:211], v[16:19]
	v_mfma_f32_16x16x32_bf16 v[16:19], v[156:159], v[212:215], v[16:19]
	v_mfma_f32_16x16x32_bf16 v[32:35], v[156:159], v[204:207], v[32:35]
	v_mfma_f32_16x16x32_bf16 v[48:51], v[156:159], v[196:199], v[48:51]
	v_mfma_f32_16x16x32_bf16 v[60:63], v[156:159], v[188:191], v[60:63]
	v_mfma_f32_16x16x32_bf16 v[56:59], v[164:167], v[188:191], v[56:59]
	v_mfma_f32_16x16x32_bf16 v[40:43], v[164:167], v[196:199], v[40:43]
	v_mfma_f32_16x16x32_bf16 v[24:27], v[164:167], v[204:207], v[24:27]
	v_mfma_f32_16x16x32_bf16 v[8:11], v[164:167], v[212:215], v[8:11]
	v_mfma_f32_16x16x32_bf16 v[4:7], v[172:175], v[212:215], v[4:7]
	v_mfma_f32_16x16x32_bf16 v[20:23], v[172:175], v[204:207], v[20:23]
	v_mfma_f32_16x16x32_bf16 v[36:39], v[172:175], v[196:199], v[36:39]
	v_mfma_f32_16x16x32_bf16 v[52:55], v[172:175], v[188:191], v[52:55]
	v_mfma_f32_16x16x32_bf16 v[44:47], v[180:183], v[188:191], v[44:47]
	v_mfma_f32_16x16x32_bf16 v[28:31], v[180:183], v[196:199], v[28:31]
	v_mfma_f32_16x16x32_bf16 v[12:15], v[180:183], v[204:207], v[12:15]
	v_mfma_f32_16x16x32_bf16 v[0:3], v[180:183], v[212:215], v[0:3]
	s_barrier
	s_add_i32 s46, s46, 2
	s_add_u32 s6, s6, 0x100
	s_addc_u32 s15, s15, 0
	s_cmp_gt_u32 s46, 13
	s_mov_b64 s[20:21], s[22:23]
	s_cbranch_scc0 .LBB0_1263
	s_and_b64 vcc, exec, s[8:9]
	s_cbranch_vccz .LBB0_1266
	s_barrier

.LBB0_1340:
	v_add_u32_e32 v166, s51, v152
	v_add_u32_e32 v182, s52, v152
	ds_read_b128 v[154:157], v166
	ds_read_b128 v[158:161], v166 offset:1024
	ds_read_b128 v[162:165], v166 offset:2048
	ds_read_b128 v[166:169], v166 offset:3072
	ds_read_b128 v[170:173], v182
	ds_read_b128 v[174:177], v182 offset:1024
	ds_read_b128 v[178:181], v182 offset:2048
	ds_read_b128 v[182:185], v182 offset:3072
	s_add_u32 s30, s10, s28
	s_addc_u32 s31, s11, s29
	s_cmp_eq_u32 s58, 60
	s_cselect_b32 s35, s23, s31
	s_cselect_b32 s34, s54, s30
	s_cselect_b32 s31, s21, s57
	s_cselect_b32 s30, s55, s56
	v_lshl_add_u64 v[186:187], s[10:11], 0, v[146:147]
	s_add_i32 m0, s44, 0xc000
	s_nop 0
	global_load_lds_dwordx4 v[186:187], off
	v_lshl_add_u64 v[186:187], s[10:11], 0, v[144:145]
	s_add_i32 m0, s44, 0xe000
	s_nop 0
	global_load_lds_dwordx4 v[186:187], off
	ds_read_b128 v[186:189], v153
	ds_read_b128 v[190:193], v153 offset:1024
	ds_read_b128 v[194:197], v153 offset:2048
	ds_read_b128 v[198:201], v153 offset:3072
	ds_read_b128 v[202:205], v153 offset:4096
	ds_read_b128 v[206:209], v153 offset:5120
	ds_read_b128 v[210:213], v153 offset:6144
	ds_read_b128 v[214:217], v153 offset:7168
	s_waitcnt vmcnt(8)
	s_waitcnt lgkmcnt(0)
	s_barrier
	s_waitcnt lgkmcnt(0)
	v_mfma_f32_16x16x32_bf16 v[124:127], v[154:157], v[186:189], v[124:127]
	v_mfma_f32_16x16x32_bf16 v[120:123], v[162:165], v[186:189], v[120:123]
	v_mfma_f32_16x16x32_bf16 v[116:119], v[170:173], v[186:189], v[116:119]
	v_mfma_f32_16x16x32_bf16 v[112:115], v[178:181], v[186:189], v[112:115]
	v_mfma_f32_16x16x32_bf16 v[96:99], v[178:181], v[194:197], v[96:99]
	v_mfma_f32_16x16x32_bf16 v[100:103], v[170:173], v[194:197], v[100:103]
	v_mfma_f32_16x16x32_bf16 v[104:107], v[162:165], v[194:197], v[104:107]
	v_mfma_f32_16x16x32_bf16 v[108:111], v[154:157], v[194:197], v[108:111]
	v_mfma_f32_16x16x32_bf16 v[92:95], v[154:157], v[202:205], v[92:95]
	v_mfma_f32_16x16x32_bf16 v[88:91], v[162:165], v[202:205], v[88:91]
	v_mfma_f32_16x16x32_bf16 v[84:87], v[170:173], v[202:205], v[84:87]
	v_mfma_f32_16x16x32_bf16 v[80:83], v[178:181], v[202:205], v[80:83]
	v_mfma_f32_16x16x32_bf16 v[64:67], v[178:181], v[210:213], v[64:67]
	v_mfma_f32_16x16x32_bf16 v[68:71], v[170:173], v[210:213], v[68:71]
	v_mfma_f32_16x16x32_bf16 v[72:75], v[162:165], v[210:213], v[72:75]
	v_mfma_f32_16x16x32_bf16 v[76:79], v[154:157], v[210:213], v[76:79]
	v_mfma_f32_16x16x32_bf16 v[76:79], v[158:161], v[214:217], v[76:79]
	v_mfma_f32_16x16x32_bf16 v[92:95], v[158:161], v[206:209], v[92:95]
	v_mfma_f32_16x16x32_bf16 v[108:111], v[158:161], v[198:201], v[108:111]
	v_mfma_f32_16x16x32_bf16 v[124:127], v[158:161], v[190:193], v[124:127]
	v_mfma_f32_16x16x32_bf16 v[120:123], v[166:169], v[190:193], v[120:123]
	v_mfma_f32_16x16x32_bf16 v[104:107], v[166:169], v[198:201], v[104:107]
	v_mfma_f32_16x16x32_bf16 v[88:91], v[166:169], v[206:209], v[88:91]
	v_mfma_f32_16x16x32_bf16 v[72:75], v[166:169], v[214:217], v[72:75]
	v_mfma_f32_16x16x32_bf16 v[68:71], v[174:177], v[214:217], v[68:71]
	v_mfma_f32_16x16x32_bf16 v[84:87], v[174:177], v[206:209], v[84:87]
	v_mfma_f32_16x16x32_bf16 v[100:103], v[174:177], v[198:201], v[100:103]
	v_mfma_f32_16x16x32_bf16 v[116:119], v[174:177], v[190:193], v[116:119]
	v_mfma_f32_16x16x32_bf16 v[112:115], v[182:185], v[190:193], v[112:115]
	v_mfma_f32_16x16x32_bf16 v[96:99], v[182:185], v[198:201], v[96:99]
	v_mfma_f32_16x16x32_bf16 v[80:83], v[182:185], v[206:209], v[80:83]
	v_mfma_f32_16x16x32_bf16 v[64:67], v[182:185], v[214:217], v[64:67]
	s_barrier
	s_add_i32 s59, s51, s43
	v_lshl_add_u64 v[218:219], s[30:31], 0, v[130:131]
	s_mov_b32 m0, s59
	v_lshl_add_u64 v[220:221], s[30:31], 0, v[134:135]
	global_load_lds_dwordx4 v[218:219], off
	s_add_i32 m0, s59, 0x2000
	s_add_u32 s60, s30, 0x100000
	s_addc_u32 s61, s31, 0
	s_add_i32 s59, s52, s43
	global_load_lds_dwordx4 v[220:221], off
	v_lshl_add_u64 v[186:187], s[60:61], 0, v[130:131]
	s_mov_b32 m0, s59
	v_lshl_add_u64 v[222:223], s[34:35], 0, v[128:129]
	global_load_lds_dwordx4 v[186:187], off
	v_lshl_add_u64 v[186:187], s[60:61], 0, v[134:135]
	s_add_i32 m0, s59, 0x2000
	v_lshl_add_u64 v[224:225], s[34:35], 0, v[132:133]
	global_load_lds_dwordx4 v[186:187], off
	s_mov_b32 m0, s44
	s_nop 0
	global_load_lds_dwordx4 v[222:223], off
	s_mov_b32 m0, s45
	s_nop 0
	global_load_lds_dwordx4 v[224:225], off
	ds_read_b128 v[186:189], v153 offset:16384
	ds_read_b128 v[190:193], v153 offset:17408
	ds_read_b128 v[194:197], v153 offset:18432
	ds_read_b128 v[198:201], v153 offset:19456
	ds_read_b128 v[202:205], v153 offset:20480
	ds_read_b128 v[206:209], v153 offset:21504
	ds_read_b128 v[210:213], v153 offset:22528
	ds_read_b128 v[214:217], v153 offset:23552
	s_waitcnt vmcnt(8)
	s_waitcnt lgkmcnt(0)
	s_barrier
	s_waitcnt lgkmcnt(0)
	v_mfma_f32_16x16x32_bf16 v[60:63], v[154:157], v[186:189], v[60:63]
	v_mfma_f32_16x16x32_bf16 v[56:59], v[162:165], v[186:189], v[56:59]
	v_mfma_f32_16x16x32_bf16 v[52:55], v[170:173], v[186:189], v[52:55]
	v_mfma_f32_16x16x32_bf16 v[48:51], v[178:181], v[186:189], v[48:51]
	v_mfma_f32_16x16x32_bf16 v[32:35], v[178:181], v[194:197], v[32:35]
	v_mfma_f32_16x16x32_bf16 v[36:39], v[170:173], v[194:197], v[36:39]
	v_mfma_f32_16x16x32_bf16 v[40:43], v[162:165], v[194:197], v[40:43]
	v_mfma_f32_16x16x32_bf16 v[44:47], v[154:157], v[194:197], v[44:47]
	v_mfma_f32_16x16x32_bf16 v[28:31], v[154:157], v[202:205], v[28:31]
	v_mfma_f32_16x16x32_bf16 v[24:27], v[162:165], v[202:205], v[24:27]
	v_mfma_f32_16x16x32_bf16 v[20:23], v[170:173], v[202:205], v[20:23]
	v_mfma_f32_16x16x32_bf16 v[16:19], v[178:181], v[202:205], v[16:19]
	v_mfma_f32_16x16x32_bf16 v[0:3], v[178:181], v[210:213], v[0:3]
	v_mfma_f32_16x16x32_bf16 v[4:7], v[170:173], v[210:213], v[4:7]
	v_mfma_f32_16x16x32_bf16 v[8:11], v[162:165], v[210:213], v[8:11]
	v_mfma_f32_16x16x32_bf16 v[12:15], v[154:157], v[210:213], v[12:15]
	v_mfma_f32_16x16x32_bf16 v[12:15], v[158:161], v[214:217], v[12:15]
	v_mfma_f32_16x16x32_bf16 v[28:31], v[158:161], v[206:209], v[28:31]
	v_mfma_f32_16x16x32_bf16 v[44:47], v[158:161], v[198:201], v[44:47]
	v_mfma_f32_16x16x32_bf16 v[60:63], v[158:161], v[190:193], v[60:63]
	v_mfma_f32_16x16x32_bf16 v[56:59], v[166:169], v[190:193], v[56:59]
	v_mfma_f32_16x16x32_bf16 v[40:43], v[166:169], v[198:201], v[40:43]
	v_mfma_f32_16x16x32_bf16 v[24:27], v[166:169], v[206:209], v[24:27]
	v_mfma_f32_16x16x32_bf16 v[8:11], v[166:169], v[214:217], v[8:11]
	v_mfma_f32_16x16x32_bf16 v[4:7], v[174:177], v[214:217], v[4:7]
	v_mfma_f32_16x16x32_bf16 v[20:23], v[174:177], v[206:209], v[20:23]
	v_mfma_f32_16x16x32_bf16 v[36:39], v[174:177], v[198:201], v[36:39]
	v_mfma_f32_16x16x32_bf16 v[52:55], v[174:177], v[190:193], v[52:55]
	v_mfma_f32_16x16x32_bf16 v[48:51], v[182:185], v[190:193], v[48:51]
	v_mfma_f32_16x16x32_bf16 v[32:35], v[182:185], v[198:201], v[32:35]
	v_mfma_f32_16x16x32_bf16 v[16:19], v[182:185], v[206:209], v[16:19]
	v_mfma_f32_16x16x32_bf16 v[0:3], v[182:185], v[214:217], v[0:3]
	s_barrier
	s_add_i32 s59, 0, 0x18000
	s_add_i32 s60, 0, 0x1c000
	v_add_u32_e32 v166, s59, v152
	v_add_u32_e32 v182, s60, v152
	ds_read_b128 v[154:157], v166
	ds_read_b128 v[158:161], v166 offset:1024
	ds_read_b128 v[162:165], v166 offset:2048
	ds_read_b128 v[166:169], v166 offset:3072
	ds_read_b128 v[170:173], v182
	ds_read_b128 v[174:177], v182 offset:1024
	ds_read_b128 v[178:181], v182 offset:2048
	ds_read_b128 v[182:185], v182 offset:3072
	s_add_u32 s34, s34, 0x100000
	s_addc_u32 s35, s35, 0
	s_mov_b32 m0, s46
	v_lshl_add_u64 v[186:187], s[34:35], 0, v[128:129]
	global_load_lds_dwordx4 v[186:187], off
	v_lshl_add_u64 v[186:187], s[34:35], 0, v[132:133]
	s_mov_b32 m0, s47
	s_nop 0
	global_load_lds_dwordx4 v[186:187], off
	ds_read_b128 v[186:189], v153 offset:32768
	ds_read_b128 v[190:193], v153 offset:33792
	ds_read_b128 v[194:197], v153 offset:34816
	ds_read_b128 v[198:201], v153 offset:35840
	ds_read_b128 v[202:205], v153 offset:36864
	ds_read_b128 v[206:209], v153 offset:37888
	ds_read_b128 v[210:213], v153 offset:38912
	ds_read_b128 v[214:217], v153 offset:39936
	s_waitcnt vmcnt(8)
	s_waitcnt lgkmcnt(0)
	s_barrier
	s_waitcnt lgkmcnt(0)
	v_mfma_f32_16x16x32_bf16 v[124:127], v[154:157], v[186:189], v[124:127]
	v_mfma_f32_16x16x32_bf16 v[120:123], v[162:165], v[186:189], v[120:123]
	v_mfma_f32_16x16x32_bf16 v[116:119], v[170:173], v[186:189], v[116:119]
	v_mfma_f32_16x16x32_bf16 v[112:115], v[178:181], v[186:189], v[112:115]
	v_mfma_f32_16x16x32_bf16 v[96:99], v[178:181], v[194:197], v[96:99]
	v_mfma_f32_16x16x32_bf16 v[100:103], v[170:173], v[194:197], v[100:103]
	v_mfma_f32_16x16x32_bf16 v[104:107], v[162:165], v[194:197], v[104:107]
	v_mfma_f32_16x16x32_bf16 v[108:111], v[154:157], v[194:197], v[108:111]
	v_mfma_f32_16x16x32_bf16 v[92:95], v[154:157], v[202:205], v[92:95]
	v_mfma_f32_16x16x32_bf16 v[88:91], v[162:165], v[202:205], v[88:91]
	v_mfma_f32_16x16x32_bf16 v[84:87], v[170:173], v[202:205], v[84:87]
	v_mfma_f32_16x16x32_bf16 v[80:83], v[178:181], v[202:205], v[80:83]
	v_mfma_f32_16x16x32_bf16 v[64:67], v[178:181], v[210:213], v[64:67]
	v_mfma_f32_16x16x32_bf16 v[68:71], v[170:173], v[210:213], v[68:71]
	v_mfma_f32_16x16x32_bf16 v[72:75], v[162:165], v[210:213], v[72:75]
	v_mfma_f32_16x16x32_bf16 v[76:79], v[154:157], v[210:213], v[76:79]
	v_mfma_f32_16x16x32_bf16 v[76:79], v[158:161], v[214:217], v[76:79]
	v_mfma_f32_16x16x32_bf16 v[92:95], v[158:161], v[206:209], v[92:95]
	v_mfma_f32_16x16x32_bf16 v[108:111], v[158:161], v[198:201], v[108:111]
	v_mfma_f32_16x16x32_bf16 v[124:127], v[158:161], v[190:193], v[124:127]
	v_mfma_f32_16x16x32_bf16 v[120:123], v[166:169], v[190:193], v[120:123]
	v_mfma_f32_16x16x32_bf16 v[104:107], v[166:169], v[198:201], v[104:107]
	v_mfma_f32_16x16x32_bf16 v[88:91], v[166:169], v[206:209], v[88:91]
	v_mfma_f32_16x16x32_bf16 v[72:75], v[166:169], v[214:217], v[72:75]
	v_mfma_f32_16x16x32_bf16 v[68:71], v[174:177], v[214:217], v[68:71]
	v_mfma_f32_16x16x32_bf16 v[84:87], v[174:177], v[206:209], v[84:87]
	v_mfma_f32_16x16x32_bf16 v[100:103], v[174:177], v[198:201], v[100:103]
	v_mfma_f32_16x16x32_bf16 v[116:119], v[174:177], v[190:193], v[116:119]
	v_mfma_f32_16x16x32_bf16 v[112:115], v[182:185], v[190:193], v[112:115]
	v_mfma_f32_16x16x32_bf16 v[96:99], v[182:185], v[198:201], v[96:99]
	v_mfma_f32_16x16x32_bf16 v[80:83], v[182:185], v[206:209], v[80:83]
	v_mfma_f32_16x16x32_bf16 v[64:67], v[182:185], v[214:217], v[64:67]
	s_barrier
	s_add_i32 s34, s59, s43
	v_lshl_add_u64 v[186:187], v[218:219], 0, s[14:15]
	s_mov_b32 m0, s34
	s_nop 0
	global_load_lds_dwordx4 v[186:187], off
	s_add_i32 m0, s34, 0x2000
	s_add_u32 s30, s30, 0x100080
	v_lshl_add_u64 v[186:187], v[220:221], 0, s[14:15]
	s_addc_u32 s31, s31, 0
	s_add_i32 s34, s60, s43
	global_load_lds_dwordx4 v[186:187], off
	v_lshl_add_u64 v[186:187], s[30:31], 0, v[130:131]
	s_mov_b32 m0, s34
	s_nop 0
	global_load_lds_dwordx4 v[186:187], off
	v_lshl_add_u64 v[186:187], s[30:31], 0, v[134:135]
	s_add_i32 m0, s34, 0x2000
	s_nop 0
	global_load_lds_dwordx4 v[186:187], off
	v_lshl_add_u64 v[186:187], v[222:223], 0, s[16:17]
	s_mov_b32 m0, s49
	s_nop 0
	global_load_lds_dwordx4 v[186:187], off
	v_lshl_add_u64 v[186:187], v[224:225], 0, s[16:17]
	s_mov_b32 m0, s50
	s_nop 0
	global_load_lds_dwordx4 v[186:187], off
	ds_read_b128 v[186:189], v153 offset:49152
	ds_read_b128 v[190:193], v153 offset:50176
	ds_read_b128 v[194:197], v153 offset:51200
	ds_read_b128 v[198:201], v153 offset:52224
	ds_read_b128 v[202:205], v153 offset:53248
	ds_read_b128 v[206:209], v153 offset:54272
	ds_read_b128 v[210:213], v153 offset:55296
	ds_read_b128 v[214:217], v153 offset:56320
	s_waitcnt vmcnt(8)
	s_waitcnt lgkmcnt(0)
	s_barrier
	s_waitcnt lgkmcnt(0)
	v_mfma_f32_16x16x32_bf16 v[60:63], v[154:157], v[186:189], v[60:63]
	v_mfma_f32_16x16x32_bf16 v[56:59], v[162:165], v[186:189], v[56:59]
	v_mfma_f32_16x16x32_bf16 v[52:55], v[170:173], v[186:189], v[52:55]
	v_mfma_f32_16x16x32_bf16 v[48:51], v[178:181], v[186:189], v[48:51]
	v_mfma_f32_16x16x32_bf16 v[32:35], v[178:181], v[194:197], v[32:35]
	v_mfma_f32_16x16x32_bf16 v[36:39], v[170:173], v[194:197], v[36:39]
	v_mfma_f32_16x16x32_bf16 v[40:43], v[162:165], v[194:197], v[40:43]
	v_mfma_f32_16x16x32_bf16 v[44:47], v[154:157], v[194:197], v[44:47]
	v_mfma_f32_16x16x32_bf16 v[28:31], v[154:157], v[202:205], v[28:31]
	v_mfma_f32_16x16x32_bf16 v[24:27], v[162:165], v[202:205], v[24:27]
	v_mfma_f32_16x16x32_bf16 v[20:23], v[170:173], v[202:205], v[20:23]
	v_mfma_f32_16x16x32_bf16 v[16:19], v[178:181], v[202:205], v[16:19]
	v_mfma_f32_16x16x32_bf16 v[0:3], v[178:181], v[210:213], v[0:3]
	v_mfma_f32_16x16x32_bf16 v[4:7], v[170:173], v[210:213], v[4:7]
	v_mfma_f32_16x16x32_bf16 v[8:11], v[162:165], v[210:213], v[8:11]
	v_mfma_f32_16x16x32_bf16 v[12:15], v[154:157], v[210:213], v[12:15]
	v_mfma_f32_16x16x32_bf16 v[12:15], v[158:161], v[214:217], v[12:15]
	v_mfma_f32_16x16x32_bf16 v[28:31], v[158:161], v[206:209], v[28:31]
	v_mfma_f32_16x16x32_bf16 v[44:47], v[158:161], v[198:201], v[44:47]
	v_mfma_f32_16x16x32_bf16 v[60:63], v[158:161], v[190:193], v[60:63]
	v_mfma_f32_16x16x32_bf16 v[56:59], v[166:169], v[190:193], v[56:59]
	v_mfma_f32_16x16x32_bf16 v[40:43], v[166:169], v[198:201], v[40:43]
	v_mfma_f32_16x16x32_bf16 v[24:27], v[166:169], v[206:209], v[24:27]
	v_mfma_f32_16x16x32_bf16 v[8:11], v[166:169], v[214:217], v[8:11]
	v_mfma_f32_16x16x32_bf16 v[4:7], v[174:177], v[214:217], v[4:7]
	v_mfma_f32_16x16x32_bf16 v[20:23], v[174:177], v[206:209], v[20:23]
	v_mfma_f32_16x16x32_bf16 v[36:39], v[174:177], v[198:201], v[36:39]
	v_mfma_f32_16x16x32_bf16 v[52:55], v[174:177], v[190:193], v[52:55]
	v_mfma_f32_16x16x32_bf16 v[48:51], v[182:185], v[190:193], v[48:51]
	v_mfma_f32_16x16x32_bf16 v[32:35], v[182:185], v[198:201], v[32:35]
	v_mfma_f32_16x16x32_bf16 v[16:19], v[182:185], v[206:209], v[16:19]
	v_mfma_f32_16x16x32_bf16 v[0:3], v[182:185], v[214:217], v[0:3]
	s_barrier
	s_add_i32 s58, s58, 2
	s_add_u32 s56, s56, 0x100
	s_addc_u32 s57, s57, 0
	s_add_u32 s28, s28, 0x1000
	s_addc_u32 s29, s29, 0
	v_lshl_add_u64 v[146:147], v[146:147], 0, s[18:19]
	s_cmp_gt_u32 s58, 61
	v_lshl_add_u64 v[144:145], v[144:145], 0, s[18:19]
	s_cbranch_scc0 .LBB0_1340
	s_andn2_b64 vcc, exec, s[4:5]
	s_cbranch_vccnz .LBB0_1332
	v_mov_b32_e32 v0, 0
	s_mov_b32 s7, s20
	s_mov_b32 s6, s22
	s_mov_b64 s[8:9], s[26:27]
	s_mov_b64 s[10:11], s[24:25]
	s_mov_b32 s48, s53
	v_mov_b32_e32 v1, v0
	v_mov_b32_e32 v2, v0
	v_mov_b32_e32 v3, v0
	v_mov_b32_e32 v4, v0
	v_mov_b32_e32 v5, v0
	v_mov_b32_e32 v6, v0
	v_mov_b32_e32 v7, v0
	v_mov_b32_e32 v16, v0
	v_mov_b32_e32 v17, v0
	v_mov_b32_e32 v18, v0
	v_mov_b32_e32 v19, v0
	v_mov_b32_e32 v20, v0
	v_mov_b32_e32 v21, v0
	v_mov_b32_e32 v22, v0
	v_mov_b32_e32 v23, v0
	v_mov_b32_e32 v32, v0
	v_mov_b32_e32 v33, v0
	v_mov_b32_e32 v34, v0
	v_mov_b32_e32 v35, v0
	v_mov_b32_e32 v36, v0
	v_mov_b32_e32 v37, v0
	v_mov_b32_e32 v38, v0
	v_mov_b32_e32 v39, v0
	v_mov_b32_e32 v48, v0
	v_mov_b32_e32 v49, v0
	v_mov_b32_e32 v50, v0
	v_mov_b32_e32 v51, v0
	v_mov_b32_e32 v52, v0
	v_mov_b32_e32 v53, v0
	v_mov_b32_e32 v54, v0
	v_mov_b32_e32 v55, v0
	v_mov_b32_e32 v8, v0
	v_mov_b32_e32 v9, v0
	v_mov_b32_e32 v10, v0
	v_mov_b32_e32 v11, v0
	v_mov_b32_e32 v12, v0
	v_mov_b32_e32 v13, v0
	v_mov_b32_e32 v14, v0
	v_mov_b32_e32 v15, v0
	v_mov_b32_e32 v24, v0
	v_mov_b32_e32 v25, v0
	v_mov_b32_e32 v26, v0
	v_mov_b32_e32 v27, v0
	v_mov_b32_e32 v28, v0
	v_mov_b32_e32 v29, v0
	v_mov_b32_e32 v30, v0
	v_mov_b32_e32 v31, v0
	v_mov_b32_e32 v40, v0
	v_mov_b32_e32 v41, v0
	v_mov_b32_e32 v42, v0
	v_mov_b32_e32 v43, v0
	v_mov_b32_e32 v44, v0
	v_mov_b32_e32 v45, v0
	v_mov_b32_e32 v46, v0
	v_mov_b32_e32 v47, v0
	v_mov_b32_e32 v56, v0
	v_mov_b32_e32 v57, v0
	v_mov_b32_e32 v58, v0
	v_mov_b32_e32 v59, v0
	v_mov_b32_e32 v60, v0
	v_mov_b32_e32 v61, v0
	v_mov_b32_e32 v62, v0
	v_mov_b32_e32 v63, v0
	v_mov_b32_e32 v64, v0
	v_mov_b32_e32 v65, v0
	v_mov_b32_e32 v66, v0
	v_mov_b32_e32 v67, v0
	v_mov_b32_e32 v68, v0
	v_mov_b32_e32 v69, v0
	v_mov_b32_e32 v70, v0
	v_mov_b32_e32 v71, v0
	v_mov_b32_e32 v80, v0
	v_mov_b32_e32 v81, v0
	v_mov_b32_e32 v82, v0
	v_mov_b32_e32 v83, v0
	v_mov_b32_e32 v84, v0
	v_mov_b32_e32 v85, v0
	v_mov_b32_e32 v86, v0
	v_mov_b32_e32 v87, v0
	v_mov_b32_e32 v96, v0
	v_mov_b32_e32 v97, v0
	v_mov_b32_e32 v98, v0
	v_mov_b32_e32 v99, v0
	v_mov_b32_e32 v100, v0
	v_mov_b32_e32 v101, v0
	v_mov_b32_e32 v102, v0
	v_mov_b32_e32 v103, v0
	v_mov_b32_e32 v112, v0
	v_mov_b32_e32 v113, v0
	v_mov_b32_e32 v114, v0
	v_mov_b32_e32 v115, v0
	v_mov_b32_e32 v116, v0
	v_mov_b32_e32 v117, v0
	v_mov_b32_e32 v118, v0
	v_mov_b32_e32 v119, v0
	v_mov_b32_e32 v72, v0
	v_mov_b32_e32 v73, v0
	v_mov_b32_e32 v74, v0
	v_mov_b32_e32 v75, v0
	v_mov_b32_e32 v76, v0
	v_mov_b32_e32 v77, v0
	v_mov_b32_e32 v78, v0
	v_mov_b32_e32 v79, v0
	v_mov_b32_e32 v88, v0
	v_mov_b32_e32 v89, v0
	v_mov_b32_e32 v90, v0
	v_mov_b32_e32 v91, v0
	v_mov_b32_e32 v92, v0
	v_mov_b32_e32 v93, v0
	v_mov_b32_e32 v94, v0
	v_mov_b32_e32 v95, v0
	v_mov_b32_e32 v104, v0
	v_mov_b32_e32 v105, v0
	v_mov_b32_e32 v106, v0
	v_mov_b32_e32 v107, v0
	v_mov_b32_e32 v108, v0
	v_mov_b32_e32 v109, v0
	v_mov_b32_e32 v110, v0
	v_mov_b32_e32 v111, v0
	v_mov_b32_e32 v120, v0
	v_mov_b32_e32 v121, v0
	v_mov_b32_e32 v122, v0
	v_mov_b32_e32 v123, v0
	v_mov_b32_e32 v124, v0
	v_mov_b32_e32 v125, v0
	v_mov_b32_e32 v126, v0
	v_mov_b32_e32 v127, v0
	s_branch .LBB0_1332

.LBB0_1435:
	ds_read_b128 v[128:131], v180
	ds_read_b128 v[132:135], v180 offset:1024
	ds_read_b128 v[136:139], v180 offset:2048
	ds_read_b128 v[140:143], v180 offset:3072
	ds_read_b128 v[144:147], v181
	ds_read_b128 v[148:151], v181 offset:1024
	ds_read_b128 v[170:173], v181 offset:2048
	ds_read_b128 v[174:177], v181 offset:3072
	s_add_u32 s26, s24, 0xfffc0080
	s_addc_u32 s27, s25, -1
	s_cmp_eq_u32 s35, 12
	s_cselect_b32 s29, s1, s27
	s_cselect_b32 s28, s19, s26
	s_cselect_b32 s27, s17, s34
	s_cselect_b32 s26, s30, s31
	v_lshl_add_u64 v[184:185], s[24:25], 0, v[162:163]
	s_add_i32 m0, s40, 0xc000
	s_nop 0
	global_load_lds_dwordx4 v[184:185], off
	v_lshl_add_u64 v[184:185], s[24:25], 0, v[164:165]
	s_add_i32 m0, s40, 0xe000
	s_nop 0
	global_load_lds_dwordx4 v[184:185], off
	ds_read_b128 v[184:187], v182
	ds_read_b128 v[188:191], v182 offset:1024
	ds_read_b128 v[192:195], v182 offset:2048
	ds_read_b128 v[196:199], v182 offset:3072
	ds_read_b128 v[200:203], v182 offset:4096
	ds_read_b128 v[204:207], v182 offset:5120
	ds_read_b128 v[208:211], v182 offset:6144
	ds_read_b128 v[212:215], v182 offset:7168
	s_waitcnt vmcnt(8)
	s_waitcnt lgkmcnt(0)
	s_barrier
	s_waitcnt lgkmcnt(0)
	v_mfma_f32_16x16x32_bf16 v[124:127], v[128:131], v[184:187], v[124:127]
	v_mfma_f32_16x16x32_bf16 v[120:123], v[136:139], v[184:187], v[120:123]
	v_mfma_f32_16x16x32_bf16 v[116:119], v[144:147], v[184:187], v[116:119]
	v_mfma_f32_16x16x32_bf16 v[112:115], v[170:173], v[184:187], v[112:115]
	v_mfma_f32_16x16x32_bf16 v[96:99], v[170:173], v[192:195], v[96:99]
	v_mfma_f32_16x16x32_bf16 v[100:103], v[144:147], v[192:195], v[100:103]
	v_mfma_f32_16x16x32_bf16 v[104:107], v[136:139], v[192:195], v[104:107]
	v_mfma_f32_16x16x32_bf16 v[108:111], v[128:131], v[192:195], v[108:111]
	v_mfma_f32_16x16x32_bf16 v[92:95], v[128:131], v[200:203], v[92:95]
	v_mfma_f32_16x16x32_bf16 v[88:91], v[136:139], v[200:203], v[88:91]
	v_mfma_f32_16x16x32_bf16 v[84:87], v[144:147], v[200:203], v[84:87]
	v_mfma_f32_16x16x32_bf16 v[80:83], v[170:173], v[200:203], v[80:83]
	v_mfma_f32_16x16x32_bf16 v[64:67], v[170:173], v[208:211], v[64:67]
	v_mfma_f32_16x16x32_bf16 v[68:71], v[144:147], v[208:211], v[68:71]
	v_mfma_f32_16x16x32_bf16 v[72:75], v[136:139], v[208:211], v[72:75]
	v_mfma_f32_16x16x32_bf16 v[76:79], v[128:131], v[208:211], v[76:79]
	v_mfma_f32_16x16x32_bf16 v[76:79], v[132:135], v[212:215], v[76:79]
	v_mfma_f32_16x16x32_bf16 v[92:95], v[132:135], v[204:207], v[92:95]
	v_mfma_f32_16x16x32_bf16 v[108:111], v[132:135], v[196:199], v[108:111]
	v_mfma_f32_16x16x32_bf16 v[124:127], v[132:135], v[188:191], v[124:127]
	v_mfma_f32_16x16x32_bf16 v[120:123], v[140:143], v[188:191], v[120:123]
	v_mfma_f32_16x16x32_bf16 v[104:107], v[140:143], v[196:199], v[104:107]
	v_mfma_f32_16x16x32_bf16 v[88:91], v[140:143], v[204:207], v[88:91]
	v_mfma_f32_16x16x32_bf16 v[72:75], v[140:143], v[212:215], v[72:75]
	v_mfma_f32_16x16x32_bf16 v[68:71], v[148:151], v[212:215], v[68:71]
	v_mfma_f32_16x16x32_bf16 v[84:87], v[148:151], v[204:207], v[84:87]
	v_mfma_f32_16x16x32_bf16 v[100:103], v[148:151], v[196:199], v[100:103]
	v_mfma_f32_16x16x32_bf16 v[116:119], v[148:151], v[188:191], v[116:119]
	v_mfma_f32_16x16x32_bf16 v[112:115], v[174:177], v[188:191], v[112:115]
	v_mfma_f32_16x16x32_bf16 v[96:99], v[174:177], v[196:199], v[96:99]
	v_mfma_f32_16x16x32_bf16 v[80:83], v[174:177], v[204:207], v[80:83]
	v_mfma_f32_16x16x32_bf16 v[64:67], v[174:177], v[212:215], v[64:67]
	s_barrier
	s_add_i32 s54, s50, s39
	v_lshl_add_u64 v[216:217], s[26:27], 0, v[154:155]
	s_mov_b32 m0, s54
	v_lshl_add_u64 v[218:219], s[26:27], 0, v[158:159]
	global_load_lds_dwordx4 v[216:217], off
	s_add_i32 m0, s54, 0x2000
	s_add_u32 s54, s26, 0x100000
	s_addc_u32 s55, s27, 0
	s_add_i32 s56, s51, s39
	global_load_lds_dwordx4 v[218:219], off
	v_lshl_add_u64 v[184:185], s[54:55], 0, v[154:155]
	s_mov_b32 m0, s56
	v_lshl_add_u64 v[220:221], s[28:29], 0, v[152:153]
	global_load_lds_dwordx4 v[184:185], off
	v_lshl_add_u64 v[184:185], s[54:55], 0, v[158:159]
	s_add_i32 m0, s56, 0x2000
	v_lshl_add_u64 v[222:223], s[28:29], 0, v[156:157]
	global_load_lds_dwordx4 v[184:185], off
	s_mov_b32 m0, s40
	s_nop 0
	global_load_lds_dwordx4 v[220:221], off
	s_mov_b32 m0, s41
	s_nop 0
	global_load_lds_dwordx4 v[222:223], off
	ds_read_b128 v[184:187], v182 offset:16384
	ds_read_b128 v[188:191], v182 offset:17408
	ds_read_b128 v[192:195], v182 offset:18432
	ds_read_b128 v[196:199], v182 offset:19456
	ds_read_b128 v[200:203], v182 offset:20480
	ds_read_b128 v[204:207], v182 offset:21504
	ds_read_b128 v[208:211], v182 offset:22528
	ds_read_b128 v[212:215], v182 offset:23552
	s_waitcnt vmcnt(8)
	s_waitcnt lgkmcnt(0)
	s_barrier
	s_waitcnt lgkmcnt(0)
	v_mfma_f32_16x16x32_bf16 v[60:63], v[128:131], v[184:187], v[60:63]
	v_mfma_f32_16x16x32_bf16 v[56:59], v[136:139], v[184:187], v[56:59]
	v_mfma_f32_16x16x32_bf16 v[52:55], v[144:147], v[184:187], v[52:55]
	v_mfma_f32_16x16x32_bf16 v[48:51], v[170:173], v[184:187], v[48:51]
	v_mfma_f32_16x16x32_bf16 v[32:35], v[170:173], v[192:195], v[32:35]
	v_mfma_f32_16x16x32_bf16 v[36:39], v[144:147], v[192:195], v[36:39]
	v_mfma_f32_16x16x32_bf16 v[40:43], v[136:139], v[192:195], v[40:43]
	v_mfma_f32_16x16x32_bf16 v[44:47], v[128:131], v[192:195], v[44:47]
	v_mfma_f32_16x16x32_bf16 v[28:31], v[128:131], v[200:203], v[28:31]
	v_mfma_f32_16x16x32_bf16 v[24:27], v[136:139], v[200:203], v[24:27]
	v_mfma_f32_16x16x32_bf16 v[20:23], v[144:147], v[200:203], v[20:23]
	v_mfma_f32_16x16x32_bf16 v[16:19], v[170:173], v[200:203], v[16:19]
	v_mfma_f32_16x16x32_bf16 v[0:3], v[170:173], v[208:211], v[0:3]
	v_mfma_f32_16x16x32_bf16 v[4:7], v[144:147], v[208:211], v[4:7]
	v_mfma_f32_16x16x32_bf16 v[8:11], v[136:139], v[208:211], v[8:11]
	v_mfma_f32_16x16x32_bf16 v[12:15], v[128:131], v[208:211], v[12:15]
	v_mfma_f32_16x16x32_bf16 v[12:15], v[132:135], v[212:215], v[12:15]
	v_mfma_f32_16x16x32_bf16 v[28:31], v[132:135], v[204:207], v[28:31]
	v_mfma_f32_16x16x32_bf16 v[44:47], v[132:135], v[196:199], v[44:47]
	v_mfma_f32_16x16x32_bf16 v[60:63], v[132:135], v[188:191], v[60:63]
	v_mfma_f32_16x16x32_bf16 v[56:59], v[140:143], v[188:191], v[56:59]
	v_mfma_f32_16x16x32_bf16 v[40:43], v[140:143], v[196:199], v[40:43]
	v_mfma_f32_16x16x32_bf16 v[24:27], v[140:143], v[204:207], v[24:27]
	v_mfma_f32_16x16x32_bf16 v[8:11], v[140:143], v[212:215], v[8:11]
	v_mfma_f32_16x16x32_bf16 v[4:7], v[148:151], v[212:215], v[4:7]
	v_mfma_f32_16x16x32_bf16 v[20:23], v[148:151], v[204:207], v[20:23]
	v_mfma_f32_16x16x32_bf16 v[36:39], v[148:151], v[196:199], v[36:39]
	v_mfma_f32_16x16x32_bf16 v[52:55], v[148:151], v[188:191], v[52:55]
	v_mfma_f32_16x16x32_bf16 v[48:51], v[174:177], v[188:191], v[48:51]
	v_mfma_f32_16x16x32_bf16 v[32:35], v[174:177], v[196:199], v[32:35]
	v_mfma_f32_16x16x32_bf16 v[16:19], v[174:177], v[204:207], v[16:19]
	v_mfma_f32_16x16x32_bf16 v[0:3], v[174:177], v[212:215], v[0:3]
	s_barrier
	s_add_i32 s54, 0, 0x18000
	s_add_i32 s55, 0, 0x1c000
	v_add_u32_e32 v140, s54, v178
	v_add_u32_e32 v174, s55, v178
	ds_read_b128 v[128:131], v140
	ds_read_b128 v[132:135], v140 offset:1024
	ds_read_b128 v[136:139], v140 offset:2048
	ds_read_b128 v[140:143], v140 offset:3072
	ds_read_b128 v[144:147], v174
	ds_read_b128 v[148:151], v174 offset:1024
	ds_read_b128 v[170:173], v174 offset:2048
	ds_read_b128 v[174:177], v174 offset:3072
	s_add_u32 s28, s28, 0x40000
	s_addc_u32 s29, s29, 0
	s_mov_b32 m0, s42
	v_lshl_add_u64 v[184:185], s[28:29], 0, v[152:153]
	global_load_lds_dwordx4 v[184:185], off
	v_lshl_add_u64 v[184:185], s[28:29], 0, v[156:157]
	s_mov_b32 m0, s43
	s_nop 0
	global_load_lds_dwordx4 v[184:185], off
	ds_read_b128 v[184:187], v182 offset:32768
	ds_read_b128 v[188:191], v182 offset:33792
	ds_read_b128 v[192:195], v182 offset:34816
	ds_read_b128 v[196:199], v182 offset:35840
	ds_read_b128 v[200:203], v182 offset:36864
	ds_read_b128 v[204:207], v182 offset:37888
	ds_read_b128 v[208:211], v182 offset:38912
	ds_read_b128 v[212:215], v182 offset:39936
	s_waitcnt vmcnt(8)
	s_waitcnt lgkmcnt(0)
	s_barrier
	s_waitcnt lgkmcnt(0)
	v_mfma_f32_16x16x32_bf16 v[124:127], v[128:131], v[184:187], v[124:127]
	v_mfma_f32_16x16x32_bf16 v[120:123], v[136:139], v[184:187], v[120:123]
	v_mfma_f32_16x16x32_bf16 v[116:119], v[144:147], v[184:187], v[116:119]
	v_mfma_f32_16x16x32_bf16 v[112:115], v[170:173], v[184:187], v[112:115]
	v_mfma_f32_16x16x32_bf16 v[96:99], v[170:173], v[192:195], v[96:99]
	v_mfma_f32_16x16x32_bf16 v[100:103], v[144:147], v[192:195], v[100:103]
	v_mfma_f32_16x16x32_bf16 v[104:107], v[136:139], v[192:195], v[104:107]
	v_mfma_f32_16x16x32_bf16 v[108:111], v[128:131], v[192:195], v[108:111]
	v_mfma_f32_16x16x32_bf16 v[92:95], v[128:131], v[200:203], v[92:95]
	v_mfma_f32_16x16x32_bf16 v[88:91], v[136:139], v[200:203], v[88:91]
	v_mfma_f32_16x16x32_bf16 v[84:87], v[144:147], v[200:203], v[84:87]
	v_mfma_f32_16x16x32_bf16 v[80:83], v[170:173], v[200:203], v[80:83]
	v_mfma_f32_16x16x32_bf16 v[64:67], v[170:173], v[208:211], v[64:67]
	v_mfma_f32_16x16x32_bf16 v[68:71], v[144:147], v[208:211], v[68:71]
	v_mfma_f32_16x16x32_bf16 v[72:75], v[136:139], v[208:211], v[72:75]
	v_mfma_f32_16x16x32_bf16 v[76:79], v[128:131], v[208:211], v[76:79]
	v_mfma_f32_16x16x32_bf16 v[76:79], v[132:135], v[212:215], v[76:79]
	v_mfma_f32_16x16x32_bf16 v[92:95], v[132:135], v[204:207], v[92:95]
	v_mfma_f32_16x16x32_bf16 v[108:111], v[132:135], v[196:199], v[108:111]
	v_mfma_f32_16x16x32_bf16 v[124:127], v[132:135], v[188:191], v[124:127]
	v_mfma_f32_16x16x32_bf16 v[120:123], v[140:143], v[188:191], v[120:123]
	v_mfma_f32_16x16x32_bf16 v[104:107], v[140:143], v[196:199], v[104:107]
	v_mfma_f32_16x16x32_bf16 v[88:91], v[140:143], v[204:207], v[88:91]
	v_mfma_f32_16x16x32_bf16 v[72:75], v[140:143], v[212:215], v[72:75]
	v_mfma_f32_16x16x32_bf16 v[68:71], v[148:151], v[212:215], v[68:71]
	v_mfma_f32_16x16x32_bf16 v[84:87], v[148:151], v[204:207], v[84:87]
	v_mfma_f32_16x16x32_bf16 v[100:103], v[148:151], v[196:199], v[100:103]
	v_mfma_f32_16x16x32_bf16 v[116:119], v[148:151], v[188:191], v[116:119]
	v_mfma_f32_16x16x32_bf16 v[112:115], v[174:177], v[188:191], v[112:115]
	v_mfma_f32_16x16x32_bf16 v[96:99], v[174:177], v[196:199], v[96:99]
	v_mfma_f32_16x16x32_bf16 v[80:83], v[174:177], v[204:207], v[80:83]
	v_mfma_f32_16x16x32_bf16 v[64:67], v[174:177], v[212:215], v[64:67]
	s_barrier
	s_add_i32 s28, s54, s39
	v_lshl_add_u64 v[184:185], v[216:217], 0, s[14:15]
	s_mov_b32 m0, s28
	s_nop 0
	global_load_lds_dwordx4 v[184:185], off
	s_add_i32 m0, s28, 0x2000
	s_add_u32 s26, s26, 0x100080
	v_lshl_add_u64 v[184:185], v[218:219], 0, s[14:15]
	s_addc_u32 s27, s27, 0
	s_add_i32 s28, s55, s39
	global_load_lds_dwordx4 v[184:185], off
	v_lshl_add_u64 v[184:185], s[26:27], 0, v[154:155]
	s_mov_b32 m0, s28
	s_nop 0
	global_load_lds_dwordx4 v[184:185], off
	v_lshl_add_u64 v[184:185], s[26:27], 0, v[158:159]
	s_add_i32 m0, s28, 0x2000
	s_nop 0
	global_load_lds_dwordx4 v[184:185], off
	v_lshl_add_u64 v[184:185], v[220:221], 0, s[14:15]
	s_mov_b32 m0, s45
	s_nop 0
	global_load_lds_dwordx4 v[184:185], off
	v_lshl_add_u64 v[184:185], v[222:223], 0, s[14:15]
	s_mov_b32 m0, s46
	s_nop 0
	global_load_lds_dwordx4 v[184:185], off
	ds_read_b128 v[184:187], v182 offset:49152
	ds_read_b128 v[188:191], v182 offset:50176
	ds_read_b128 v[192:195], v182 offset:51200
	ds_read_b128 v[196:199], v182 offset:52224
	ds_read_b128 v[200:203], v182 offset:53248
	ds_read_b128 v[204:207], v182 offset:54272
	ds_read_b128 v[208:211], v182 offset:55296
	ds_read_b128 v[212:215], v182 offset:56320
	s_waitcnt vmcnt(8)
	s_waitcnt lgkmcnt(0)
	s_barrier
	s_waitcnt lgkmcnt(0)
	v_mfma_f32_16x16x32_bf16 v[60:63], v[128:131], v[184:187], v[60:63]
	v_mfma_f32_16x16x32_bf16 v[56:59], v[136:139], v[184:187], v[56:59]
	v_mfma_f32_16x16x32_bf16 v[52:55], v[144:147], v[184:187], v[52:55]
	v_mfma_f32_16x16x32_bf16 v[48:51], v[170:173], v[184:187], v[48:51]
	v_mfma_f32_16x16x32_bf16 v[32:35], v[170:173], v[192:195], v[32:35]
	v_mfma_f32_16x16x32_bf16 v[36:39], v[144:147], v[192:195], v[36:39]
	v_mfma_f32_16x16x32_bf16 v[40:43], v[136:139], v[192:195], v[40:43]
	v_mfma_f32_16x16x32_bf16 v[44:47], v[128:131], v[192:195], v[44:47]
	v_mfma_f32_16x16x32_bf16 v[28:31], v[128:131], v[200:203], v[28:31]
	v_mfma_f32_16x16x32_bf16 v[24:27], v[136:139], v[200:203], v[24:27]
	v_mfma_f32_16x16x32_bf16 v[20:23], v[144:147], v[200:203], v[20:23]
	v_mfma_f32_16x16x32_bf16 v[16:19], v[170:173], v[200:203], v[16:19]
	v_mfma_f32_16x16x32_bf16 v[0:3], v[170:173], v[208:211], v[0:3]
	v_mfma_f32_16x16x32_bf16 v[4:7], v[144:147], v[208:211], v[4:7]
	v_mfma_f32_16x16x32_bf16 v[8:11], v[136:139], v[208:211], v[8:11]
	v_mfma_f32_16x16x32_bf16 v[12:15], v[128:131], v[208:211], v[12:15]
	v_mfma_f32_16x16x32_bf16 v[12:15], v[132:135], v[212:215], v[12:15]
	v_mfma_f32_16x16x32_bf16 v[28:31], v[132:135], v[204:207], v[28:31]
	v_mfma_f32_16x16x32_bf16 v[44:47], v[132:135], v[196:199], v[44:47]
	v_mfma_f32_16x16x32_bf16 v[60:63], v[132:135], v[188:191], v[60:63]
	v_mfma_f32_16x16x32_bf16 v[56:59], v[140:143], v[188:191], v[56:59]
	v_mfma_f32_16x16x32_bf16 v[40:43], v[140:143], v[196:199], v[40:43]
	v_mfma_f32_16x16x32_bf16 v[24:27], v[140:143], v[204:207], v[24:27]
	v_mfma_f32_16x16x32_bf16 v[8:11], v[140:143], v[212:215], v[8:11]
	v_mfma_f32_16x16x32_bf16 v[4:7], v[148:151], v[212:215], v[4:7]
	v_mfma_f32_16x16x32_bf16 v[20:23], v[148:151], v[204:207], v[20:23]
	v_mfma_f32_16x16x32_bf16 v[36:39], v[148:151], v[196:199], v[36:39]
	v_mfma_f32_16x16x32_bf16 v[52:55], v[148:151], v[188:191], v[52:55]
	v_mfma_f32_16x16x32_bf16 v[48:51], v[174:177], v[188:191], v[48:51]
	v_mfma_f32_16x16x32_bf16 v[32:35], v[174:177], v[196:199], v[32:35]
	v_mfma_f32_16x16x32_bf16 v[16:19], v[174:177], v[204:207], v[16:19]
	v_mfma_f32_16x16x32_bf16 v[0:3], v[174:177], v[212:215], v[0:3]
	s_barrier
	s_add_i32 s35, s35, 2
	s_add_u32 s24, s24, 0x100
	s_addc_u32 s25, s25, 0
	s_add_u32 s31, s31, 0x100
	s_addc_u32 s34, s34, 0
	s_cmp_gt_u32 s35, 13
	s_cbranch_scc0 .LBB0_1435
	s_and_b64 vcc, exec, s[8:9]
	s_cbranch_vccz .LBB0_1438
	s_barrier

.LBB0_1543:
	ds_read_b128 v[128:131], v167
	ds_read_b128 v[154:157], v167 offset:1024
	ds_read_b128 v[172:175], v167 offset:2048
	ds_read_b128 v[176:179], v167 offset:3072
	ds_read_b128 v[180:183], v168
	ds_read_b128 v[184:187], v168 offset:1024
	ds_read_b128 v[188:191], v168 offset:2048
	ds_read_b128 v[192:195], v168 offset:3072
	s_add_u32 s22, s20, 0x1000
	s_addc_u32 s23, s21, 0
	s_cmp_eq_u32 s54, 60
	s_cselect_b32 s27, s13, s23
	s_cselect_b32 s26, s50, s22
	s_cselect_b32 s25, s11, s53
	s_cselect_b32 s24, s51, s52
	v_lshl_add_u64 v[160:161], s[20:21], 0, v[144:145]
	s_add_i32 m0, s19, 0xc000
	s_nop 0
	global_load_lds_dwordx4 v[160:161], off
	v_lshl_add_u64 v[160:161], s[20:21], 0, v[146:147]
	s_add_i32 m0, s19, 0xe000
	s_nop 0
	global_load_lds_dwordx4 v[160:161], off
	ds_read_b128 v[196:199], v169
	ds_read_b128 v[200:203], v169 offset:1024
	ds_read_b128 v[204:207], v169 offset:2048
	ds_read_b128 v[208:211], v169 offset:3072
	ds_read_b128 v[212:215], v169 offset:4096
	ds_read_b128 v[216:219], v169 offset:5120
	ds_read_b128 v[220:223], v169 offset:6144
	ds_read_b128 v[224:227], v169 offset:7168
	s_waitcnt vmcnt(8)
	s_waitcnt lgkmcnt(0)
	s_barrier
	s_waitcnt lgkmcnt(0)
	v_mfma_f32_16x16x32_bf16 v[124:127], v[128:131], v[196:199], v[124:127]
	v_mfma_f32_16x16x32_bf16 v[120:123], v[172:175], v[196:199], v[120:123]
	v_mfma_f32_16x16x32_bf16 v[116:119], v[180:183], v[196:199], v[116:119]
	v_mfma_f32_16x16x32_bf16 v[112:115], v[188:191], v[196:199], v[112:115]
	v_mfma_f32_16x16x32_bf16 v[96:99], v[188:191], v[204:207], v[96:99]
	v_mfma_f32_16x16x32_bf16 v[100:103], v[180:183], v[204:207], v[100:103]
	v_mfma_f32_16x16x32_bf16 v[104:107], v[172:175], v[204:207], v[104:107]
	v_mfma_f32_16x16x32_bf16 v[108:111], v[128:131], v[204:207], v[108:111]
	v_mfma_f32_16x16x32_bf16 v[92:95], v[128:131], v[212:215], v[92:95]
	v_mfma_f32_16x16x32_bf16 v[88:91], v[172:175], v[212:215], v[88:91]
	v_mfma_f32_16x16x32_bf16 v[84:87], v[180:183], v[212:215], v[84:87]
	v_mfma_f32_16x16x32_bf16 v[80:83], v[188:191], v[212:215], v[80:83]
	v_mfma_f32_16x16x32_bf16 v[64:67], v[188:191], v[220:223], v[64:67]
	v_mfma_f32_16x16x32_bf16 v[68:71], v[180:183], v[220:223], v[68:71]
	v_mfma_f32_16x16x32_bf16 v[72:75], v[172:175], v[220:223], v[72:75]
	v_mfma_f32_16x16x32_bf16 v[76:79], v[128:131], v[220:223], v[76:79]
	v_mfma_f32_16x16x32_bf16 v[76:79], v[154:157], v[224:227], v[76:79]
	v_mfma_f32_16x16x32_bf16 v[92:95], v[154:157], v[216:219], v[92:95]
	v_mfma_f32_16x16x32_bf16 v[108:111], v[154:157], v[208:211], v[108:111]
	v_mfma_f32_16x16x32_bf16 v[124:127], v[154:157], v[200:203], v[124:127]
	v_mfma_f32_16x16x32_bf16 v[120:123], v[176:179], v[200:203], v[120:123]
	v_mfma_f32_16x16x32_bf16 v[104:107], v[176:179], v[208:211], v[104:107]
	v_mfma_f32_16x16x32_bf16 v[88:91], v[176:179], v[216:219], v[88:91]
	v_mfma_f32_16x16x32_bf16 v[72:75], v[176:179], v[224:227], v[72:75]
	v_mfma_f32_16x16x32_bf16 v[68:71], v[184:187], v[224:227], v[68:71]
	v_mfma_f32_16x16x32_bf16 v[84:87], v[184:187], v[216:219], v[84:87]
	v_mfma_f32_16x16x32_bf16 v[100:103], v[184:187], v[208:211], v[100:103]
	v_mfma_f32_16x16x32_bf16 v[116:119], v[184:187], v[200:203], v[116:119]
	v_mfma_f32_16x16x32_bf16 v[112:115], v[192:195], v[200:203], v[112:115]
	v_mfma_f32_16x16x32_bf16 v[96:99], v[192:195], v[208:211], v[96:99]
	v_mfma_f32_16x16x32_bf16 v[80:83], v[192:195], v[216:219], v[80:83]
	v_mfma_f32_16x16x32_bf16 v[64:67], v[192:195], v[224:227], v[64:67]
	s_barrier
	s_add_i32 s20, s45, s30
	v_lshl_add_u64 v[160:161], s[24:25], 0, v[134:135]
	s_mov_b32 m0, s20
	v_lshl_add_u64 v[164:165], s[24:25], 0, v[138:139]
	global_load_lds_dwordx4 v[160:161], off
	s_add_i32 m0, s20, 0x2000
	s_add_u32 s20, s24, 0x100000
	s_addc_u32 s21, s25, 0
	s_add_i32 s55, s46, s30
	global_load_lds_dwordx4 v[164:165], off
	v_lshl_add_u64 v[196:197], s[20:21], 0, v[134:135]
	s_mov_b32 m0, s55
	v_lshl_add_u64 v[228:229], s[26:27], 0, v[132:133]
	global_load_lds_dwordx4 v[196:197], off
	v_lshl_add_u64 v[196:197], s[20:21], 0, v[138:139]
	s_add_i32 m0, s55, 0x2000
	v_lshl_add_u64 v[230:231], s[26:27], 0, v[136:137]
	global_load_lds_dwordx4 v[196:197], off
	s_mov_b32 m0, s19
	s_nop 0
	global_load_lds_dwordx4 v[228:229], off
	s_mov_b32 m0, s36
	s_nop 0
	global_load_lds_dwordx4 v[230:231], off
	ds_read_b128 v[196:199], v169 offset:16384
	ds_read_b128 v[200:203], v169 offset:17408
	ds_read_b128 v[204:207], v169 offset:18432
	ds_read_b128 v[208:211], v169 offset:19456
	ds_read_b128 v[212:215], v169 offset:20480
	ds_read_b128 v[216:219], v169 offset:21504
	ds_read_b128 v[220:223], v169 offset:22528
	ds_read_b128 v[224:227], v169 offset:23552
	s_waitcnt vmcnt(8)
	s_waitcnt lgkmcnt(0)
	s_barrier
	s_waitcnt lgkmcnt(0)
	v_mfma_f32_16x16x32_bf16 v[60:63], v[128:131], v[196:199], v[60:63]
	v_mfma_f32_16x16x32_bf16 v[56:59], v[172:175], v[196:199], v[56:59]
	v_mfma_f32_16x16x32_bf16 v[52:55], v[180:183], v[196:199], v[52:55]
	v_mfma_f32_16x16x32_bf16 v[48:51], v[188:191], v[196:199], v[48:51]
	v_mfma_f32_16x16x32_bf16 v[32:35], v[188:191], v[204:207], v[32:35]
	v_mfma_f32_16x16x32_bf16 v[36:39], v[180:183], v[204:207], v[36:39]
	v_mfma_f32_16x16x32_bf16 v[40:43], v[172:175], v[204:207], v[40:43]
	v_mfma_f32_16x16x32_bf16 v[44:47], v[128:131], v[204:207], v[44:47]
	v_mfma_f32_16x16x32_bf16 v[28:31], v[128:131], v[212:215], v[28:31]
	v_mfma_f32_16x16x32_bf16 v[24:27], v[172:175], v[212:215], v[24:27]
	v_mfma_f32_16x16x32_bf16 v[20:23], v[180:183], v[212:215], v[20:23]
	v_mfma_f32_16x16x32_bf16 v[16:19], v[188:191], v[212:215], v[16:19]
	v_mfma_f32_16x16x32_bf16 v[0:3], v[188:191], v[220:223], v[0:3]
	v_mfma_f32_16x16x32_bf16 v[4:7], v[180:183], v[220:223], v[4:7]
	v_mfma_f32_16x16x32_bf16 v[8:11], v[172:175], v[220:223], v[8:11]
	v_mfma_f32_16x16x32_bf16 v[12:15], v[128:131], v[220:223], v[12:15]
	v_mfma_f32_16x16x32_bf16 v[12:15], v[154:157], v[224:227], v[12:15]
	v_mfma_f32_16x16x32_bf16 v[28:31], v[154:157], v[216:219], v[28:31]
	v_mfma_f32_16x16x32_bf16 v[44:47], v[154:157], v[208:211], v[44:47]
	v_mfma_f32_16x16x32_bf16 v[60:63], v[154:157], v[200:203], v[60:63]
	v_mfma_f32_16x16x32_bf16 v[56:59], v[176:179], v[200:203], v[56:59]
	v_mfma_f32_16x16x32_bf16 v[40:43], v[176:179], v[208:211], v[40:43]
	v_mfma_f32_16x16x32_bf16 v[24:27], v[176:179], v[216:219], v[24:27]
	v_mfma_f32_16x16x32_bf16 v[8:11], v[176:179], v[224:227], v[8:11]
	v_mfma_f32_16x16x32_bf16 v[4:7], v[184:187], v[224:227], v[4:7]
	v_mfma_f32_16x16x32_bf16 v[20:23], v[184:187], v[216:219], v[20:23]
	v_mfma_f32_16x16x32_bf16 v[36:39], v[184:187], v[208:211], v[36:39]
	v_mfma_f32_16x16x32_bf16 v[52:55], v[184:187], v[200:203], v[52:55]
	v_mfma_f32_16x16x32_bf16 v[48:51], v[192:195], v[200:203], v[48:51]
	v_mfma_f32_16x16x32_bf16 v[32:35], v[192:195], v[208:211], v[32:35]
	v_mfma_f32_16x16x32_bf16 v[16:19], v[192:195], v[216:219], v[16:19]
	v_mfma_f32_16x16x32_bf16 v[0:3], v[192:195], v[224:227], v[0:3]
	s_barrier
	s_add_i32 s55, 0, 0x18000
	v_add_u32_e32 v153, s55, v159
	s_add_i32 s56, 0, 0x1c000
	ds_read_b128 v[128:131], v153
	ds_read_b128 v[154:157], v153 offset:1024
	ds_read_b128 v[172:175], v153 offset:2048
	ds_read_b128 v[176:179], v153 offset:3072
	v_add_u32_e32 v153, s56, v159
	ds_read_b128 v[180:183], v153
	ds_read_b128 v[184:187], v153 offset:1024
	ds_read_b128 v[188:191], v153 offset:2048
	ds_read_b128 v[192:195], v153 offset:3072
	s_add_u32 s20, s26, 0x100000
	s_addc_u32 s21, s27, 0
	s_mov_b32 m0, s37
	v_lshl_add_u64 v[196:197], s[20:21], 0, v[132:133]
	global_load_lds_dwordx4 v[196:197], off
	v_lshl_add_u64 v[196:197], s[20:21], 0, v[136:137]
	s_mov_b32 m0, s38
	s_nop 0
	global_load_lds_dwordx4 v[196:197], off
	ds_read_b128 v[196:199], v169 offset:32768
	ds_read_b128 v[200:203], v169 offset:33792
	ds_read_b128 v[204:207], v169 offset:34816
	ds_read_b128 v[208:211], v169 offset:35840
	ds_read_b128 v[212:215], v169 offset:36864
	ds_read_b128 v[216:219], v169 offset:37888
	ds_read_b128 v[220:223], v169 offset:38912
	ds_read_b128 v[224:227], v169 offset:39936
	s_waitcnt vmcnt(8)
	s_waitcnt lgkmcnt(0)
	s_barrier
	s_waitcnt lgkmcnt(0)
	v_mfma_f32_16x16x32_bf16 v[124:127], v[128:131], v[196:199], v[124:127]
	v_mfma_f32_16x16x32_bf16 v[120:123], v[172:175], v[196:199], v[120:123]
	v_mfma_f32_16x16x32_bf16 v[116:119], v[180:183], v[196:199], v[116:119]
	v_mfma_f32_16x16x32_bf16 v[112:115], v[188:191], v[196:199], v[112:115]
	v_mfma_f32_16x16x32_bf16 v[96:99], v[188:191], v[204:207], v[96:99]
	v_mfma_f32_16x16x32_bf16 v[100:103], v[180:183], v[204:207], v[100:103]
	v_mfma_f32_16x16x32_bf16 v[104:107], v[172:175], v[204:207], v[104:107]
	v_mfma_f32_16x16x32_bf16 v[108:111], v[128:131], v[204:207], v[108:111]
	v_mfma_f32_16x16x32_bf16 v[92:95], v[128:131], v[212:215], v[92:95]
	v_mfma_f32_16x16x32_bf16 v[88:91], v[172:175], v[212:215], v[88:91]
	v_mfma_f32_16x16x32_bf16 v[84:87], v[180:183], v[212:215], v[84:87]
	v_mfma_f32_16x16x32_bf16 v[80:83], v[188:191], v[212:215], v[80:83]
	v_mfma_f32_16x16x32_bf16 v[64:67], v[188:191], v[220:223], v[64:67]
	v_mfma_f32_16x16x32_bf16 v[68:71], v[180:183], v[220:223], v[68:71]
	v_mfma_f32_16x16x32_bf16 v[72:75], v[172:175], v[220:223], v[72:75]
	v_mfma_f32_16x16x32_bf16 v[76:79], v[128:131], v[220:223], v[76:79]
	v_mfma_f32_16x16x32_bf16 v[76:79], v[154:157], v[224:227], v[76:79]
	v_mfma_f32_16x16x32_bf16 v[92:95], v[154:157], v[216:219], v[92:95]
	v_mfma_f32_16x16x32_bf16 v[108:111], v[154:157], v[208:211], v[108:111]
	v_mfma_f32_16x16x32_bf16 v[124:127], v[154:157], v[200:203], v[124:127]
	v_mfma_f32_16x16x32_bf16 v[120:123], v[176:179], v[200:203], v[120:123]
	v_mfma_f32_16x16x32_bf16 v[104:107], v[176:179], v[208:211], v[104:107]
	v_mfma_f32_16x16x32_bf16 v[88:91], v[176:179], v[216:219], v[88:91]
	v_mfma_f32_16x16x32_bf16 v[72:75], v[176:179], v[224:227], v[72:75]
	v_mfma_f32_16x16x32_bf16 v[68:71], v[184:187], v[224:227], v[68:71]
	v_mfma_f32_16x16x32_bf16 v[84:87], v[184:187], v[216:219], v[84:87]
	v_mfma_f32_16x16x32_bf16 v[100:103], v[184:187], v[208:211], v[100:103]
	v_mfma_f32_16x16x32_bf16 v[116:119], v[184:187], v[200:203], v[116:119]
	v_mfma_f32_16x16x32_bf16 v[112:115], v[192:195], v[200:203], v[112:115]
	v_mfma_f32_16x16x32_bf16 v[96:99], v[192:195], v[208:211], v[96:99]
	v_mfma_f32_16x16x32_bf16 v[80:83], v[192:195], v[216:219], v[80:83]
	v_mfma_f32_16x16x32_bf16 v[64:67], v[192:195], v[224:227], v[64:67]
	s_barrier
	s_add_i32 s20, s55, s30
	v_lshl_add_u64 v[160:161], v[160:161], 0, s[8:9]
	s_mov_b32 m0, s20
	s_nop 0
	global_load_lds_dwordx4 v[160:161], off
	s_add_i32 m0, s20, 0x2000
	s_add_u32 s20, s24, 0x100800
	v_lshl_add_u64 v[160:161], v[164:165], 0, s[8:9]
	s_addc_u32 s21, s25, 0
	s_add_i32 s24, s56, s30
	global_load_lds_dwordx4 v[160:161], off
	v_lshl_add_u64 v[160:161], s[20:21], 0, v[134:135]
	s_mov_b32 m0, s24
	s_nop 0
	global_load_lds_dwordx4 v[160:161], off
	v_lshl_add_u64 v[160:161], s[20:21], 0, v[138:139]
	s_add_i32 m0, s24, 0x2000
	s_nop 0
	global_load_lds_dwordx4 v[160:161], off
	v_lshl_add_u64 v[160:161], v[228:229], 0, s[8:9]
	s_mov_b32 m0, s41
	s_nop 0
	global_load_lds_dwordx4 v[160:161], off
	v_lshl_add_u64 v[160:161], v[230:231], 0, s[8:9]
	s_mov_b32 m0, s42
	s_nop 0
	global_load_lds_dwordx4 v[160:161], off
	ds_read_b128 v[196:199], v169 offset:49152
	ds_read_b128 v[200:203], v169 offset:50176
	ds_read_b128 v[204:207], v169 offset:51200
	ds_read_b128 v[208:211], v169 offset:52224
	ds_read_b128 v[212:215], v169 offset:53248
	ds_read_b128 v[216:219], v169 offset:54272
	ds_read_b128 v[220:223], v169 offset:55296
	ds_read_b128 v[224:227], v169 offset:56320
	s_waitcnt vmcnt(8)
	s_waitcnt lgkmcnt(0)
	s_barrier
	s_waitcnt lgkmcnt(0)
	v_mfma_f32_16x16x32_bf16 v[60:63], v[128:131], v[196:199], v[60:63]
	v_mfma_f32_16x16x32_bf16 v[56:59], v[172:175], v[196:199], v[56:59]
	v_mfma_f32_16x16x32_bf16 v[52:55], v[180:183], v[196:199], v[52:55]
	v_mfma_f32_16x16x32_bf16 v[48:51], v[188:191], v[196:199], v[48:51]
	v_mfma_f32_16x16x32_bf16 v[32:35], v[188:191], v[204:207], v[32:35]
	v_mfma_f32_16x16x32_bf16 v[36:39], v[180:183], v[204:207], v[36:39]
	v_mfma_f32_16x16x32_bf16 v[40:43], v[172:175], v[204:207], v[40:43]
	v_mfma_f32_16x16x32_bf16 v[44:47], v[128:131], v[204:207], v[44:47]
	v_mfma_f32_16x16x32_bf16 v[28:31], v[128:131], v[212:215], v[28:31]
	v_mfma_f32_16x16x32_bf16 v[24:27], v[172:175], v[212:215], v[24:27]
	v_mfma_f32_16x16x32_bf16 v[20:23], v[180:183], v[212:215], v[20:23]
	v_mfma_f32_16x16x32_bf16 v[16:19], v[188:191], v[212:215], v[16:19]
	v_mfma_f32_16x16x32_bf16 v[0:3], v[188:191], v[220:223], v[0:3]
	v_mfma_f32_16x16x32_bf16 v[4:7], v[180:183], v[220:223], v[4:7]
	v_mfma_f32_16x16x32_bf16 v[8:11], v[172:175], v[220:223], v[8:11]
	v_mfma_f32_16x16x32_bf16 v[12:15], v[128:131], v[220:223], v[12:15]
	v_mfma_f32_16x16x32_bf16 v[12:15], v[154:157], v[224:227], v[12:15]
	v_mfma_f32_16x16x32_bf16 v[28:31], v[154:157], v[216:219], v[28:31]
	v_mfma_f32_16x16x32_bf16 v[44:47], v[154:157], v[208:211], v[44:47]
	v_mfma_f32_16x16x32_bf16 v[60:63], v[154:157], v[200:203], v[60:63]
	v_mfma_f32_16x16x32_bf16 v[56:59], v[176:179], v[200:203], v[56:59]
	v_mfma_f32_16x16x32_bf16 v[40:43], v[176:179], v[208:211], v[40:43]
	v_mfma_f32_16x16x32_bf16 v[24:27], v[176:179], v[216:219], v[24:27]
	v_mfma_f32_16x16x32_bf16 v[8:11], v[176:179], v[224:227], v[8:11]
	v_mfma_f32_16x16x32_bf16 v[4:7], v[184:187], v[224:227], v[4:7]
	v_mfma_f32_16x16x32_bf16 v[20:23], v[184:187], v[216:219], v[20:23]
	v_mfma_f32_16x16x32_bf16 v[36:39], v[184:187], v[208:211], v[36:39]
	v_mfma_f32_16x16x32_bf16 v[52:55], v[184:187], v[200:203], v[52:55]
	v_mfma_f32_16x16x32_bf16 v[48:51], v[192:195], v[200:203], v[48:51]
	v_mfma_f32_16x16x32_bf16 v[32:35], v[192:195], v[208:211], v[32:35]
	v_mfma_f32_16x16x32_bf16 v[16:19], v[192:195], v[216:219], v[16:19]
	v_mfma_f32_16x16x32_bf16 v[0:3], v[192:195], v[224:227], v[0:3]
	s_barrier
	s_add_i32 s54, s54, 2
	s_add_u32 s52, s52, 0x1000
	s_addc_u32 s53, s53, 0
	s_cmp_gt_u32 s54, 61
	s_mov_b64 s[20:21], s[22:23]
	s_cbranch_scc0 .LBB0_1543
	s_and_b64 vcc, exec, s[4:5]
	s_cbranch_vccz .LBB0_1546
	s_barrier

.LBB0_1625:
	ds_read_b128 v[128:131], v177
	ds_read_b128 v[132:135], v177 offset:1024
	ds_read_b128 v[136:139], v177 offset:2048
	ds_read_b128 v[140:143], v177 offset:3072
	ds_read_b128 v[144:147], v178
	ds_read_b128 v[148:151], v178 offset:1024
	ds_read_b128 v[170:173], v178 offset:2048
	ds_read_b128 v[182:185], v178 offset:3072
	s_add_u32 s24, s22, 0xffc00800
	s_addc_u32 s25, s23, -1
	s_cmpk_eq_i32 s57, 0xfc
	s_cselect_b32 s27, s29, s25
	s_cselect_b32 s26, s53, s24
	s_cselect_b32 s25, s17, s56
	s_cselect_b32 s24, s54, s55
	v_lshl_add_u64 v[186:187], s[22:23], 0, v[162:163]
	s_add_i32 m0, s38, 0xc000
	s_nop 0
	global_load_lds_dwordx4 v[186:187], off
	v_lshl_add_u64 v[186:187], s[22:23], 0, v[164:165]
	s_add_i32 m0, s38, 0xe000
	s_nop 0
	global_load_lds_dwordx4 v[186:187], off
	ds_read_b128 v[186:189], v179
	ds_read_b128 v[190:193], v179 offset:1024
	ds_read_b128 v[194:197], v179 offset:2048
	ds_read_b128 v[198:201], v179 offset:3072
	ds_read_b128 v[202:205], v179 offset:4096
	ds_read_b128 v[206:209], v179 offset:5120
	ds_read_b128 v[210:213], v179 offset:6144
	ds_read_b128 v[214:217], v179 offset:7168
	s_waitcnt vmcnt(8)
	s_waitcnt lgkmcnt(0)
	s_barrier
	s_waitcnt lgkmcnt(0)
	v_mfma_f32_16x16x32_bf16 v[124:127], v[128:131], v[186:189], v[124:127]
	v_mfma_f32_16x16x32_bf16 v[120:123], v[136:139], v[186:189], v[120:123]
	v_mfma_f32_16x16x32_bf16 v[116:119], v[144:147], v[186:189], v[116:119]
	v_mfma_f32_16x16x32_bf16 v[112:115], v[170:173], v[186:189], v[112:115]
	v_mfma_f32_16x16x32_bf16 v[96:99], v[170:173], v[194:197], v[96:99]
	v_mfma_f32_16x16x32_bf16 v[100:103], v[144:147], v[194:197], v[100:103]
	v_mfma_f32_16x16x32_bf16 v[104:107], v[136:139], v[194:197], v[104:107]
	v_mfma_f32_16x16x32_bf16 v[108:111], v[128:131], v[194:197], v[108:111]
	v_mfma_f32_16x16x32_bf16 v[92:95], v[128:131], v[202:205], v[92:95]
	v_mfma_f32_16x16x32_bf16 v[88:91], v[136:139], v[202:205], v[88:91]
	v_mfma_f32_16x16x32_bf16 v[84:87], v[144:147], v[202:205], v[84:87]
	v_mfma_f32_16x16x32_bf16 v[80:83], v[170:173], v[202:205], v[80:83]
	v_mfma_f32_16x16x32_bf16 v[64:67], v[170:173], v[210:213], v[64:67]
	v_mfma_f32_16x16x32_bf16 v[68:71], v[144:147], v[210:213], v[68:71]
	v_mfma_f32_16x16x32_bf16 v[72:75], v[136:139], v[210:213], v[72:75]
	v_mfma_f32_16x16x32_bf16 v[76:79], v[128:131], v[210:213], v[76:79]
	v_mfma_f32_16x16x32_bf16 v[76:79], v[132:135], v[214:217], v[76:79]
	v_mfma_f32_16x16x32_bf16 v[92:95], v[132:135], v[206:209], v[92:95]
	v_mfma_f32_16x16x32_bf16 v[108:111], v[132:135], v[198:201], v[108:111]
	v_mfma_f32_16x16x32_bf16 v[124:127], v[132:135], v[190:193], v[124:127]
	v_mfma_f32_16x16x32_bf16 v[120:123], v[140:143], v[190:193], v[120:123]
	v_mfma_f32_16x16x32_bf16 v[104:107], v[140:143], v[198:201], v[104:107]
	v_mfma_f32_16x16x32_bf16 v[88:91], v[140:143], v[206:209], v[88:91]
	v_mfma_f32_16x16x32_bf16 v[72:75], v[140:143], v[214:217], v[72:75]
	v_mfma_f32_16x16x32_bf16 v[68:71], v[148:151], v[214:217], v[68:71]
	v_mfma_f32_16x16x32_bf16 v[84:87], v[148:151], v[206:209], v[84:87]
	v_mfma_f32_16x16x32_bf16 v[100:103], v[148:151], v[198:201], v[100:103]
	v_mfma_f32_16x16x32_bf16 v[116:119], v[148:151], v[190:193], v[116:119]
	v_mfma_f32_16x16x32_bf16 v[112:115], v[182:185], v[190:193], v[112:115]
	v_mfma_f32_16x16x32_bf16 v[96:99], v[182:185], v[198:201], v[96:99]
	v_mfma_f32_16x16x32_bf16 v[80:83], v[182:185], v[206:209], v[80:83]
	v_mfma_f32_16x16x32_bf16 v[64:67], v[182:185], v[214:217], v[64:67]
	s_barrier
	s_add_i32 s58, s48, s37
	v_lshl_add_u64 v[218:219], s[24:25], 0, v[154:155]
	s_mov_b32 m0, s58
	v_lshl_add_u64 v[220:221], s[24:25], 0, v[158:159]
	global_load_lds_dwordx4 v[218:219], off
	s_add_i32 m0, s58, 0x2000
	s_add_u32 s58, s24, 0x400000
	s_addc_u32 s59, s25, 0
	s_add_i32 s60, s49, s37
	global_load_lds_dwordx4 v[220:221], off
	v_lshl_add_u64 v[186:187], s[58:59], 0, v[154:155]
	s_mov_b32 m0, s60
	v_lshl_add_u64 v[222:223], s[26:27], 0, v[152:153]
	global_load_lds_dwordx4 v[186:187], off
	v_lshl_add_u64 v[186:187], s[58:59], 0, v[158:159]
	s_add_i32 m0, s60, 0x2000
	v_lshl_add_u64 v[224:225], s[26:27], 0, v[156:157]
	global_load_lds_dwordx4 v[186:187], off
	s_mov_b32 m0, s38
	s_nop 0
	global_load_lds_dwordx4 v[222:223], off
	s_mov_b32 m0, s39
	s_nop 0
	global_load_lds_dwordx4 v[224:225], off
	ds_read_b128 v[186:189], v179 offset:16384
	ds_read_b128 v[190:193], v179 offset:17408
	ds_read_b128 v[194:197], v179 offset:18432
	ds_read_b128 v[198:201], v179 offset:19456
	ds_read_b128 v[202:205], v179 offset:20480
	ds_read_b128 v[206:209], v179 offset:21504
	ds_read_b128 v[210:213], v179 offset:22528
	ds_read_b128 v[214:217], v179 offset:23552
	s_waitcnt vmcnt(8)
	s_waitcnt lgkmcnt(0)
	s_barrier
	s_waitcnt lgkmcnt(0)
	v_mfma_f32_16x16x32_bf16 v[60:63], v[128:131], v[186:189], v[60:63]
	v_mfma_f32_16x16x32_bf16 v[56:59], v[136:139], v[186:189], v[56:59]
	v_mfma_f32_16x16x32_bf16 v[52:55], v[144:147], v[186:189], v[52:55]
	v_mfma_f32_16x16x32_bf16 v[48:51], v[170:173], v[186:189], v[48:51]
	v_mfma_f32_16x16x32_bf16 v[32:35], v[170:173], v[194:197], v[32:35]
	v_mfma_f32_16x16x32_bf16 v[36:39], v[144:147], v[194:197], v[36:39]
	v_mfma_f32_16x16x32_bf16 v[40:43], v[136:139], v[194:197], v[40:43]
	v_mfma_f32_16x16x32_bf16 v[44:47], v[128:131], v[194:197], v[44:47]
	v_mfma_f32_16x16x32_bf16 v[28:31], v[128:131], v[202:205], v[28:31]
	v_mfma_f32_16x16x32_bf16 v[24:27], v[136:139], v[202:205], v[24:27]
	v_mfma_f32_16x16x32_bf16 v[20:23], v[144:147], v[202:205], v[20:23]
	v_mfma_f32_16x16x32_bf16 v[16:19], v[170:173], v[202:205], v[16:19]
	v_mfma_f32_16x16x32_bf16 v[0:3], v[170:173], v[210:213], v[0:3]
	v_mfma_f32_16x16x32_bf16 v[4:7], v[144:147], v[210:213], v[4:7]
	v_mfma_f32_16x16x32_bf16 v[8:11], v[136:139], v[210:213], v[8:11]
	v_mfma_f32_16x16x32_bf16 v[12:15], v[128:131], v[210:213], v[12:15]
	v_mfma_f32_16x16x32_bf16 v[12:15], v[132:135], v[214:217], v[12:15]
	v_mfma_f32_16x16x32_bf16 v[28:31], v[132:135], v[206:209], v[28:31]
	v_mfma_f32_16x16x32_bf16 v[44:47], v[132:135], v[198:201], v[44:47]
	v_mfma_f32_16x16x32_bf16 v[60:63], v[132:135], v[190:193], v[60:63]
	v_mfma_f32_16x16x32_bf16 v[56:59], v[140:143], v[190:193], v[56:59]
	v_mfma_f32_16x16x32_bf16 v[40:43], v[140:143], v[198:201], v[40:43]
	v_mfma_f32_16x16x32_bf16 v[24:27], v[140:143], v[206:209], v[24:27]
	v_mfma_f32_16x16x32_bf16 v[8:11], v[140:143], v[214:217], v[8:11]
	v_mfma_f32_16x16x32_bf16 v[4:7], v[148:151], v[214:217], v[4:7]
	v_mfma_f32_16x16x32_bf16 v[20:23], v[148:151], v[206:209], v[20:23]
	v_mfma_f32_16x16x32_bf16 v[36:39], v[148:151], v[198:201], v[36:39]
	v_mfma_f32_16x16x32_bf16 v[52:55], v[148:151], v[190:193], v[52:55]
	v_mfma_f32_16x16x32_bf16 v[48:51], v[182:185], v[190:193], v[48:51]
	v_mfma_f32_16x16x32_bf16 v[32:35], v[182:185], v[198:201], v[32:35]
	v_mfma_f32_16x16x32_bf16 v[16:19], v[182:185], v[206:209], v[16:19]
	v_mfma_f32_16x16x32_bf16 v[0:3], v[182:185], v[214:217], v[0:3]
	s_barrier
	s_add_i32 s58, 0, 0x18000
	s_add_i32 s59, 0, 0x1c000
	v_add_u32_e32 v140, s58, v174
	v_add_u32_e32 v181, s59, v174
	ds_read_b128 v[128:131], v140
	ds_read_b128 v[132:135], v140 offset:1024
	ds_read_b128 v[136:139], v140 offset:2048
	ds_read_b128 v[140:143], v140 offset:3072
	ds_read_b128 v[144:147], v181
	ds_read_b128 v[148:151], v181 offset:1024
	ds_read_b128 v[170:173], v181 offset:2048
	ds_read_b128 v[182:185], v181 offset:3072
	s_add_u32 s26, s26, 0x400000
	s_addc_u32 s27, s27, 0
	s_mov_b32 m0, s40
	v_lshl_add_u64 v[186:187], s[26:27], 0, v[152:153]
	global_load_lds_dwordx4 v[186:187], off
	v_lshl_add_u64 v[186:187], s[26:27], 0, v[156:157]
	s_mov_b32 m0, s41
	s_nop 0
	global_load_lds_dwordx4 v[186:187], off
	ds_read_b128 v[186:189], v179 offset:32768
	ds_read_b128 v[190:193], v179 offset:33792
	ds_read_b128 v[194:197], v179 offset:34816
	ds_read_b128 v[198:201], v179 offset:35840
	ds_read_b128 v[202:205], v179 offset:36864
	ds_read_b128 v[206:209], v179 offset:37888
	ds_read_b128 v[210:213], v179 offset:38912
	ds_read_b128 v[214:217], v179 offset:39936
	s_waitcnt vmcnt(8)
	s_waitcnt lgkmcnt(0)
	s_barrier
	s_waitcnt lgkmcnt(0)
	v_mfma_f32_16x16x32_bf16 v[124:127], v[128:131], v[186:189], v[124:127]
	v_mfma_f32_16x16x32_bf16 v[120:123], v[136:139], v[186:189], v[120:123]
	v_mfma_f32_16x16x32_bf16 v[116:119], v[144:147], v[186:189], v[116:119]
	v_mfma_f32_16x16x32_bf16 v[112:115], v[170:173], v[186:189], v[112:115]
	v_mfma_f32_16x16x32_bf16 v[96:99], v[170:173], v[194:197], v[96:99]
	v_mfma_f32_16x16x32_bf16 v[100:103], v[144:147], v[194:197], v[100:103]
	v_mfma_f32_16x16x32_bf16 v[104:107], v[136:139], v[194:197], v[104:107]
	v_mfma_f32_16x16x32_bf16 v[108:111], v[128:131], v[194:197], v[108:111]
	v_mfma_f32_16x16x32_bf16 v[92:95], v[128:131], v[202:205], v[92:95]
	v_mfma_f32_16x16x32_bf16 v[88:91], v[136:139], v[202:205], v[88:91]
	v_mfma_f32_16x16x32_bf16 v[84:87], v[144:147], v[202:205], v[84:87]
	v_mfma_f32_16x16x32_bf16 v[80:83], v[170:173], v[202:205], v[80:83]
	v_mfma_f32_16x16x32_bf16 v[64:67], v[170:173], v[210:213], v[64:67]
	v_mfma_f32_16x16x32_bf16 v[68:71], v[144:147], v[210:213], v[68:71]
	v_mfma_f32_16x16x32_bf16 v[72:75], v[136:139], v[210:213], v[72:75]
	v_mfma_f32_16x16x32_bf16 v[76:79], v[128:131], v[210:213], v[76:79]
	v_mfma_f32_16x16x32_bf16 v[76:79], v[132:135], v[214:217], v[76:79]
	v_mfma_f32_16x16x32_bf16 v[92:95], v[132:135], v[206:209], v[92:95]
	v_mfma_f32_16x16x32_bf16 v[108:111], v[132:135], v[198:201], v[108:111]
	v_mfma_f32_16x16x32_bf16 v[124:127], v[132:135], v[190:193], v[124:127]
	v_mfma_f32_16x16x32_bf16 v[120:123], v[140:143], v[190:193], v[120:123]
	v_mfma_f32_16x16x32_bf16 v[104:107], v[140:143], v[198:201], v[104:107]
	v_mfma_f32_16x16x32_bf16 v[88:91], v[140:143], v[206:209], v[88:91]
	v_mfma_f32_16x16x32_bf16 v[72:75], v[140:143], v[214:217], v[72:75]
	v_mfma_f32_16x16x32_bf16 v[68:71], v[148:151], v[214:217], v[68:71]
	v_mfma_f32_16x16x32_bf16 v[84:87], v[148:151], v[206:209], v[84:87]
	v_mfma_f32_16x16x32_bf16 v[100:103], v[148:151], v[198:201], v[100:103]
	v_mfma_f32_16x16x32_bf16 v[116:119], v[148:151], v[190:193], v[116:119]
	v_mfma_f32_16x16x32_bf16 v[112:115], v[182:185], v[190:193], v[112:115]
	v_mfma_f32_16x16x32_bf16 v[96:99], v[182:185], v[198:201], v[96:99]
	v_mfma_f32_16x16x32_bf16 v[80:83], v[182:185], v[206:209], v[80:83]
	v_mfma_f32_16x16x32_bf16 v[64:67], v[182:185], v[214:217], v[64:67]
	s_barrier
	s_add_i32 s26, s58, s37
	v_lshl_add_u64 v[186:187], v[218:219], 0, s[14:15]
	s_mov_b32 m0, s26
	s_nop 0
	global_load_lds_dwordx4 v[186:187], off
	s_add_i32 m0, s26, 0x2000
	s_add_u32 s24, s24, 0x400800
	v_lshl_add_u64 v[186:187], v[220:221], 0, s[14:15]
	s_addc_u32 s25, s25, 0
	s_add_i32 s26, s59, s37
	global_load_lds_dwordx4 v[186:187], off
	v_lshl_add_u64 v[186:187], s[24:25], 0, v[154:155]
	s_mov_b32 m0, s26
	s_nop 0
	global_load_lds_dwordx4 v[186:187], off
	v_lshl_add_u64 v[186:187], s[24:25], 0, v[158:159]
	s_add_i32 m0, s26, 0x2000
	s_nop 0
	global_load_lds_dwordx4 v[186:187], off
	v_lshl_add_u64 v[186:187], v[222:223], 0, s[14:15]
	s_mov_b32 m0, s43
	s_nop 0
	global_load_lds_dwordx4 v[186:187], off
	v_lshl_add_u64 v[186:187], v[224:225], 0, s[14:15]
	s_mov_b32 m0, s44
	s_nop 0
	global_load_lds_dwordx4 v[186:187], off
	ds_read_b128 v[186:189], v179 offset:49152
	ds_read_b128 v[190:193], v179 offset:50176
	ds_read_b128 v[194:197], v179 offset:51200
	ds_read_b128 v[198:201], v179 offset:52224
	ds_read_b128 v[202:205], v179 offset:53248
	ds_read_b128 v[206:209], v179 offset:54272
	ds_read_b128 v[210:213], v179 offset:55296
	ds_read_b128 v[214:217], v179 offset:56320
	s_waitcnt vmcnt(8)
	s_waitcnt lgkmcnt(0)
	s_barrier
	s_waitcnt lgkmcnt(0)
	v_mfma_f32_16x16x32_bf16 v[60:63], v[128:131], v[186:189], v[60:63]
	v_mfma_f32_16x16x32_bf16 v[56:59], v[136:139], v[186:189], v[56:59]
	v_mfma_f32_16x16x32_bf16 v[52:55], v[144:147], v[186:189], v[52:55]
	v_mfma_f32_16x16x32_bf16 v[48:51], v[170:173], v[186:189], v[48:51]
	v_mfma_f32_16x16x32_bf16 v[32:35], v[170:173], v[194:197], v[32:35]
	v_mfma_f32_16x16x32_bf16 v[36:39], v[144:147], v[194:197], v[36:39]
	v_mfma_f32_16x16x32_bf16 v[40:43], v[136:139], v[194:197], v[40:43]
	v_mfma_f32_16x16x32_bf16 v[44:47], v[128:131], v[194:197], v[44:47]
	v_mfma_f32_16x16x32_bf16 v[28:31], v[128:131], v[202:205], v[28:31]
	v_mfma_f32_16x16x32_bf16 v[24:27], v[136:139], v[202:205], v[24:27]
	v_mfma_f32_16x16x32_bf16 v[20:23], v[144:147], v[202:205], v[20:23]
	v_mfma_f32_16x16x32_bf16 v[16:19], v[170:173], v[202:205], v[16:19]
	v_mfma_f32_16x16x32_bf16 v[0:3], v[170:173], v[210:213], v[0:3]
	v_mfma_f32_16x16x32_bf16 v[4:7], v[144:147], v[210:213], v[4:7]
	v_mfma_f32_16x16x32_bf16 v[8:11], v[136:139], v[210:213], v[8:11]
	v_mfma_f32_16x16x32_bf16 v[12:15], v[128:131], v[210:213], v[12:15]
	v_mfma_f32_16x16x32_bf16 v[12:15], v[132:135], v[214:217], v[12:15]
	v_mfma_f32_16x16x32_bf16 v[28:31], v[132:135], v[206:209], v[28:31]
	v_mfma_f32_16x16x32_bf16 v[44:47], v[132:135], v[198:201], v[44:47]
	v_mfma_f32_16x16x32_bf16 v[60:63], v[132:135], v[190:193], v[60:63]
	v_mfma_f32_16x16x32_bf16 v[56:59], v[140:143], v[190:193], v[56:59]
	v_mfma_f32_16x16x32_bf16 v[40:43], v[140:143], v[198:201], v[40:43]
	v_mfma_f32_16x16x32_bf16 v[24:27], v[140:143], v[206:209], v[24:27]
	v_mfma_f32_16x16x32_bf16 v[8:11], v[140:143], v[214:217], v[8:11]
	v_mfma_f32_16x16x32_bf16 v[4:7], v[148:151], v[214:217], v[4:7]
	v_mfma_f32_16x16x32_bf16 v[20:23], v[148:151], v[206:209], v[20:23]
	v_mfma_f32_16x16x32_bf16 v[36:39], v[148:151], v[198:201], v[36:39]
	v_mfma_f32_16x16x32_bf16 v[52:55], v[148:151], v[190:193], v[52:55]
	v_mfma_f32_16x16x32_bf16 v[48:51], v[182:185], v[190:193], v[48:51]
	v_mfma_f32_16x16x32_bf16 v[32:35], v[182:185], v[198:201], v[32:35]
	v_mfma_f32_16x16x32_bf16 v[16:19], v[182:185], v[206:209], v[16:19]
	v_mfma_f32_16x16x32_bf16 v[0:3], v[182:185], v[214:217], v[0:3]
	s_barrier
	s_add_i32 s57, s57, 2
	s_add_u32 s22, s22, 0x1000
	s_addc_u32 s23, s23, 0
	s_add_u32 s55, s55, 0x1000
	s_addc_u32 s56, s56, 0
	s_cmpk_gt_u32 s57, 0xfd
	s_cbranch_scc0 .LBB0_1625
	s_and_b64 vcc, exec, s[6:7]
	s_cbranch_vccz .LBB0_1628
	s_barrier
